# v43 plus s_setprio 1 for the trailing wave half (waves 4-7) during the six GEMM epilogues, reset at the K-loop head
# baseline (speedup 1.0000x reference)
; #define PG8_STAGE(bufoff, gbase, voff) do { _Pragma("unroll") for (int _i = 0; _i < 2; ++_i) \
;         __builtin_amdgcn_global_load_lds((const unsigned*)((const char*)(gbase) + (voff)[_i]), (PG8_LAS unsigned*)(lds + (bufoff) + ldsw + _i * 8192), 16, 0, 0); } while (0)
; #define PG8_LDA(dst, b, h) do { _Pragma("unroll") for (int m = 0; m < 4; ++m) _Pragma("unroll") for (int k = 0; k < 2; ++k) dst[m][k] = *(const PG8_LAS bf16x8*)(lds + PG8_SA(b, h) + aoff + m * 2048 + k * 1024); } while (0)
; #define PG8_LDB(dst, b, h) do { _Pragma("unroll") for (int n = 0; n < 2; ++n) _Pragma("unroll") for (int k = 0; k < 2; ++k) dst[n][k] = *(const PG8_LAS bf16x8*)(lds + PG8_SB(b, h) + boff + n * 2048 + k * 1024); } while (0)
; #define PG8_MMA(ai, bj, At, Bt) do { __builtin_amdgcn_s_setprio(1); _Pragma("unroll") for (int m = 0; m < 4; ++m) _Pragma("unroll") for (int n = 0; n < 2; ++n) _Pragma("unroll") for (int k = 0; k < 2; ++k) \
;         acc[ai][bj][m][n] = __builtin_amdgcn_mfma_f32_16x16x32_bf16(Bt[n][k], At[m][k], acc[ai][bj][m][n], 0, 0, 0); __builtin_amdgcn_s_setprio(0); } while (0)
; #define PG8_WAIT_V(n) asm volatile("s_waitcnt vmcnt(" #n ")" ::: "memory")
; #define PG8_WAIT_L(n) asm volatile("s_waitcnt lgkmcnt(" #n ")" ::: "memory")
; template <class Epi, class Sched, bool ALIGN_EPI = false, bool SP2 = false>
; __device__ __forceinline__ void gemm_phase(PG8_LAS unsigned char* lds, const Gemm g, const Sched& S, const Epi& E, int tid_in) {
;     ...
;             const bool last = (t == nt - 2);
;             const char* a1 = cA + (size_t)(t + 1) * kstep;
;             const char* a2 = last ? nA : cA + (size_t)(t + 2) * kstep; const char* b2 = last ? nB : cB + (size_t)(t + 2) * kstep;
;             const char* a3 = a2 + kstep; const char* b3 = b2 + kstep;
;             if (last && has_next) S.a_ready(nxt);
;             if constexpr (SP2) {
;             PG8_LDB(B0, 0, 0); PG8_LDB(B1, 0, 1); PG8_SCHED; PG8_LDA(At, 0, 0); PG8_STAGE(PG8_SA(1, 1), a1 + hstep, voffA);
;             PG8_WAIT_V(8); PG8_WAIT_L(0); PG8_BAR; PG8_MMA(0, 0, At, B0); PG8_MMA(0, 1, At, B1); PG8_BAR; PG8_SCHED;
;             PG8_LDA(At, 0, 1); PG8_STAGE(PG8_SB(0, 0), b2, voffB); PG8_STAGE(PG8_SB(0, 1), b2 + hstep, voffB); PG8_STAGE(PG8_SA(0, 0), a2, voffA);
;             PG8_WAIT_V(8); PG8_WAIT_L(0); PG8_BAR; PG8_MMA(1, 0, At, B0); PG8_MMA(1, 1, At, B1); PG8_BAR; PG8_SCHED;
.LBB0_296:
	s_setprio 0
	s_add_u32 s20, s2, 0xfffc0080
	s_addc_u32 s21, s3, -1
	s_add_i32 s45, 0, 0x10000
	s_cmp_eq_u32 s44, 12
	s_cselect_b32 s23, s15, s21
	s_cselect_b32 s22, s40, s20
	s_cselect_b32 s21, s13, s43
	s_cselect_b32 s20, s41, s42
	s_add_i32 s48, 0, 0x14000
	v_add_u32_e32 v156, s45, v145
	v_add_u32_e32 v172, s48, v145
	ds_read_b128 v[140:143], v156
	ds_read_b128 v[148:151], v156 offset:1024
	ds_read_b128 v[152:155], v156 offset:2048
	ds_read_b128 v[156:159], v156 offset:3072
	ds_read_b128 v[160:163], v172
	ds_read_b128 v[164:167], v172 offset:1024
	ds_read_b128 v[168:171], v172 offset:2048
	ds_read_b128 v[172:175], v172 offset:3072
	v_lshl_add_u64 v[192:193], s[2:3], 0, v[136:137]
	s_add_i32 m0, s29, 0xc000
	ds_read_b128 v[176:179], v147
	ds_read_b128 v[180:183], v147 offset:1024
	ds_read_b128 v[184:187], v147 offset:2048
	ds_read_b128 v[188:191], v147 offset:3072
	ds_read_b128 v[204:207], v147 offset:4096
	ds_read_b128 v[208:211], v147 offset:5120
	ds_read_b128 v[212:215], v147 offset:6144
	ds_read_b128 v[216:219], v147 offset:7168
	global_load_lds_dwordx4 v[192:193], off
	v_lshl_add_u64 v[192:193], s[2:3], 0, v[138:139]
	s_add_i32 m0, s29, 0xe000
	s_nop 0
	global_load_lds_dwordx4 v[192:193], off
	s_waitcnt vmcnt(8)
	s_waitcnt lgkmcnt(0)
	s_barrier
	s_setprio 1
	s_waitcnt lgkmcnt(0)
	v_mfma_f32_16x16x32_bf16 v[126:129], v[140:143], v[176:179], v[126:129]
	v_mfma_f32_16x16x32_bf16 v[118:121], v[152:155], v[176:179], v[118:121]
	v_mfma_f32_16x16x32_bf16 v[110:113], v[140:143], v[184:187], v[110:113]
	v_mfma_f32_16x16x32_bf16 v[102:105], v[152:155], v[184:187], v[102:105]
	v_mfma_f32_16x16x32_bf16 v[94:97], v[140:143], v[204:207], v[94:97]
	v_mfma_f32_16x16x32_bf16 v[90:93], v[152:155], v[204:207], v[90:93]
	v_mfma_f32_16x16x32_bf16 v[78:81], v[140:143], v[212:215], v[78:81]
	v_mfma_f32_16x16x32_bf16 v[74:77], v[152:155], v[212:215], v[74:77]
	v_mfma_f32_16x16x32_bf16 v[126:129], v[148:151], v[180:183], v[126:129]
	v_mfma_f32_16x16x32_bf16 v[118:121], v[156:159], v[180:183], v[118:121]
	v_mfma_f32_16x16x32_bf16 v[110:113], v[148:151], v[188:191], v[110:113]
	v_mfma_f32_16x16x32_bf16 v[102:105], v[156:159], v[188:191], v[102:105]
	v_mfma_f32_16x16x32_bf16 v[94:97], v[148:151], v[208:211], v[94:97]
	v_mfma_f32_16x16x32_bf16 v[90:93], v[156:159], v[208:211], v[90:93]
	v_mfma_f32_16x16x32_bf16 v[78:81], v[148:151], v[216:219], v[78:81]
	v_mfma_f32_16x16x32_bf16 v[74:77], v[156:159], v[216:219], v[74:77]
	s_setprio 0
	s_setprio 1
	v_mfma_f32_16x16x32_bf16 v[122:125], v[160:163], v[176:179], v[122:125]
	v_mfma_f32_16x16x32_bf16 v[114:117], v[168:171], v[176:179], v[114:117]
	v_mfma_f32_16x16x32_bf16 v[106:109], v[160:163], v[184:187], v[106:109]
	v_mfma_f32_16x16x32_bf16 v[98:101], v[168:171], v[184:187], v[98:101]
	v_mfma_f32_16x16x32_bf16 v[86:89], v[160:163], v[204:207], v[86:89]
	v_mfma_f32_16x16x32_bf16 v[82:85], v[168:171], v[204:207], v[82:85]
	v_mfma_f32_16x16x32_bf16 v[70:73], v[160:163], v[212:215], v[70:73]
	v_mfma_f32_16x16x32_bf16 v[66:69], v[168:171], v[212:215], v[66:69]
	v_mfma_f32_16x16x32_bf16 v[122:125], v[164:167], v[180:183], v[122:125]
	v_mfma_f32_16x16x32_bf16 v[114:117], v[172:175], v[180:183], v[114:117]
	v_mfma_f32_16x16x32_bf16 v[106:109], v[164:167], v[188:191], v[106:109]
	v_mfma_f32_16x16x32_bf16 v[98:101], v[172:175], v[188:191], v[98:101]
	v_mfma_f32_16x16x32_bf16 v[86:89], v[164:167], v[208:211], v[86:89]
	v_mfma_f32_16x16x32_bf16 v[82:85], v[172:175], v[208:211], v[82:85]
	v_mfma_f32_16x16x32_bf16 v[70:73], v[164:167], v[216:219], v[70:73]
	v_mfma_f32_16x16x32_bf16 v[66:69], v[172:175], v[216:219], v[66:69]
	s_setprio 0
	s_barrier
	s_add_i32 s45, s45, s28
	v_lshl_add_u64 v[192:193], s[20:21], 0, v[32:33]
	s_mov_b32 m0, s45
	ds_read_b128 v[176:179], v147 offset:16384
	ds_read_b128 v[180:183], v147 offset:17408
	ds_read_b128 v[184:187], v147 offset:18432
	ds_read_b128 v[188:191], v147 offset:19456
	ds_read_b128 v[204:207], v147 offset:20480
	ds_read_b128 v[208:211], v147 offset:21504
	ds_read_b128 v[212:215], v147 offset:22528
	ds_read_b128 v[216:219], v147 offset:23552
	global_load_lds_dwordx4 v[192:193], off
	s_add_i32 m0, s45, 0x2000
	s_add_u32 s46, s20, 0x40000
	v_lshl_add_u64 v[220:221], s[20:21], 0, v[130:131]
	s_addc_u32 s47, s21, 0
	s_add_i32 s45, s48, s28
	global_load_lds_dwordx4 v[220:221], off
	v_lshl_add_u64 v[222:223], s[46:47], 0, v[32:33]
	s_mov_b32 m0, s45
	v_lshl_add_u64 v[224:225], s[22:23], 0, v[132:133]
	global_load_lds_dwordx4 v[222:223], off
	v_lshl_add_u64 v[222:223], s[46:47], 0, v[130:131]
	s_add_i32 m0, s45, 0x2000
	s_nop 0
	global_load_lds_dwordx4 v[222:223], off
	v_lshl_add_u64 v[222:223], s[22:23], 0, v[134:135]
	s_mov_b32 m0, s29
	s_nop 0
	global_load_lds_dwordx4 v[222:223], off
	s_mov_b32 m0, s30
	s_nop 0
	global_load_lds_dwordx4 v[224:225], off
	s_waitcnt vmcnt(8)
	s_waitcnt lgkmcnt(0)
	s_barrier
; #define PG8_STAGE(bufoff, gbase, voff) do { _Pragma("unroll") for (int _i = 0; _i < 2; ++_i) \
;         __builtin_amdgcn_global_load_lds((const unsigned*)((const char*)(gbase) + (voff)[_i]), (PG8_LAS unsigned*)(lds + (bufoff) + ldsw + _i * 8192), 16, 0, 0); } while (0)
; #define PG8_LDA(dst, b, h) do { _Pragma("unroll") for (int m = 0; m < 4; ++m) _Pragma("unroll") for (int k = 0; k < 2; ++k) dst[m][k] = *(const PG8_LAS bf16x8*)(lds + PG8_SA(b, h) + aoff + m * 2048 + k * 1024); } while (0)
; #define PG8_LDB(dst, b, h) do { _Pragma("unroll") for (int n = 0; n < 2; ++n) _Pragma("unroll") for (int k = 0; k < 2; ++k) dst[n][k] = *(const PG8_LAS bf16x8*)(lds + PG8_SB(b, h) + boff + n * 2048 + k * 1024); } while (0)
; #define PG8_MMA(ai, bj, At, Bt) do { __builtin_amdgcn_s_setprio(1); _Pragma("unroll") for (int m = 0; m < 4; ++m) _Pragma("unroll") for (int n = 0; n < 2; ++n) _Pragma("unroll") for (int k = 0; k < 2; ++k) \
;         acc[ai][bj][m][n] = __builtin_amdgcn_mfma_f32_16x16x32_bf16(Bt[n][k], At[m][k], acc[ai][bj][m][n], 0, 0, 0); __builtin_amdgcn_s_setprio(0); } while (0)
; #define PG8_WAIT_V(n) asm volatile("s_waitcnt vmcnt(" #n ")" ::: "memory")
; #define PG8_WAIT_L(n) asm volatile("s_waitcnt lgkmcnt(" #n ")" ::: "memory")
; #define PG8_BAR __builtin_amdgcn_s_barrier()
; #define PG8_SCHED __builtin_amdgcn_sched_barrier(0)
; template <class Epi, class Sched, bool ALIGN_EPI = false, bool SP2 = false>
; __device__ __forceinline__ void gemm_phase(PG8_LAS unsigned char* lds, const Gemm g, const Sched& S, const Epi& E, int tid_in) {
;     ...
;             PG8_WAIT_V(8); PG8_WAIT_L(0); PG8_BAR; PG8_MMA(1, 0, At, B0); PG8_MMA(1, 1, At, B1); PG8_BAR; PG8_SCHED;
;             PG8_LDB(B0, 1, 0); PG8_LDB(B1, 1, 1); PG8_SCHED; PG8_LDA(At, 1, 0); PG8_STAGE(PG8_SA(0, 1), a2 + hstep, voffA);
;             PG8_WAIT_V(8); PG8_WAIT_L(0); PG8_BAR; PG8_MMA(0, 0, At, B0); PG8_MMA(0, 1, At, B1); PG8_BAR; PG8_SCHED;
	s_setprio 1
	s_waitcnt lgkmcnt(0)
	v_mfma_f32_16x16x32_bf16 v[62:65], v[140:143], v[176:179], v[62:65]
	v_mfma_f32_16x16x32_bf16 v[58:61], v[152:155], v[176:179], v[58:61]
	v_mfma_f32_16x16x32_bf16 v[46:49], v[140:143], v[184:187], v[46:49]
	v_mfma_f32_16x16x32_bf16 v[42:45], v[152:155], v[184:187], v[42:45]
	v_mfma_f32_16x16x32_bf16 v[28:31], v[140:143], v[204:207], v[28:31]
	v_mfma_f32_16x16x32_bf16 v[24:27], v[152:155], v[204:207], v[24:27]
	v_mfma_f32_16x16x32_bf16 v[12:15], v[140:143], v[212:215], v[12:15]
	v_mfma_f32_16x16x32_bf16 v[8:11], v[152:155], v[212:215], v[8:11]
	v_mfma_f32_16x16x32_bf16 v[62:65], v[148:151], v[180:183], v[62:65]
	v_mfma_f32_16x16x32_bf16 v[58:61], v[156:159], v[180:183], v[58:61]
	v_mfma_f32_16x16x32_bf16 v[46:49], v[148:151], v[188:191], v[46:49]
	v_mfma_f32_16x16x32_bf16 v[42:45], v[156:159], v[188:191], v[42:45]
	v_mfma_f32_16x16x32_bf16 v[28:31], v[148:151], v[208:211], v[28:31]
	v_mfma_f32_16x16x32_bf16 v[24:27], v[156:159], v[208:211], v[24:27]
	v_mfma_f32_16x16x32_bf16 v[12:15], v[148:151], v[216:219], v[12:15]
	v_mfma_f32_16x16x32_bf16 v[8:11], v[156:159], v[216:219], v[8:11]
	s_setprio 0
	s_setprio 1
	v_mfma_f32_16x16x32_bf16 v[54:57], v[160:163], v[176:179], v[54:57]
	v_mfma_f32_16x16x32_bf16 v[50:53], v[168:171], v[176:179], v[50:53]
	v_mfma_f32_16x16x32_bf16 v[38:41], v[160:163], v[184:187], v[38:41]
	v_mfma_f32_16x16x32_bf16 v[34:37], v[168:171], v[184:187], v[34:37]
	v_mfma_f32_16x16x32_bf16 v[20:23], v[160:163], v[204:207], v[20:23]
	v_mfma_f32_16x16x32_bf16 v[16:19], v[168:171], v[204:207], v[16:19]
	v_mfma_f32_16x16x32_bf16 v[4:7], v[160:163], v[212:215], v[4:7]
	v_mfma_f32_16x16x32_bf16 v[0:3], v[168:171], v[212:215], v[0:3]
	v_mfma_f32_16x16x32_bf16 v[54:57], v[164:167], v[180:183], v[54:57]
	v_mfma_f32_16x16x32_bf16 v[50:53], v[172:175], v[180:183], v[50:53]
	v_mfma_f32_16x16x32_bf16 v[38:41], v[164:167], v[188:191], v[38:41]
	v_mfma_f32_16x16x32_bf16 v[34:37], v[172:175], v[188:191], v[34:37]
	v_mfma_f32_16x16x32_bf16 v[20:23], v[164:167], v[208:211], v[20:23]
	v_mfma_f32_16x16x32_bf16 v[16:19], v[172:175], v[208:211], v[16:19]
	v_mfma_f32_16x16x32_bf16 v[4:7], v[164:167], v[216:219], v[4:7]
	v_mfma_f32_16x16x32_bf16 v[0:3], v[172:175], v[216:219], v[0:3]
	s_setprio 0
	s_barrier
	s_add_i32 s45, 0, 0x18000
	s_add_i32 s46, 0, 0x1c000
	v_add_u32_e32 v156, s45, v145
	v_add_u32_e32 v172, s46, v145
	ds_read_b128 v[140:143], v156
	ds_read_b128 v[148:151], v156 offset:1024
	ds_read_b128 v[152:155], v156 offset:2048
	ds_read_b128 v[156:159], v156 offset:3072
	ds_read_b128 v[160:163], v172
	ds_read_b128 v[164:167], v172 offset:1024
	ds_read_b128 v[168:171], v172 offset:2048
	ds_read_b128 v[172:175], v172 offset:3072
	s_add_u32 s22, s22, 0x40000
	s_addc_u32 s23, s23, 0
	s_mov_b32 m0, s31
	v_lshl_add_u64 v[226:227], s[22:23], 0, v[134:135]
	ds_read_b128 v[176:179], v147 offset:32768
	ds_read_b128 v[180:183], v147 offset:33792
	ds_read_b128 v[184:187], v147 offset:34816
	ds_read_b128 v[188:191], v147 offset:35840
	ds_read_b128 v[204:207], v147 offset:36864
	ds_read_b128 v[208:211], v147 offset:37888
	ds_read_b128 v[212:215], v147 offset:38912
	ds_read_b128 v[216:219], v147 offset:39936
	global_load_lds_dwordx4 v[226:227], off
	v_lshl_add_u64 v[226:227], s[22:23], 0, v[132:133]
	s_mov_b32 m0, s34
	s_nop 0
	global_load_lds_dwordx4 v[226:227], off
	s_waitcnt vmcnt(8)
	s_waitcnt lgkmcnt(0)
	s_barrier
	s_setprio 1
	s_waitcnt lgkmcnt(0)
	v_mfma_f32_16x16x32_bf16 v[126:129], v[140:143], v[176:179], v[126:129]
	v_mfma_f32_16x16x32_bf16 v[118:121], v[152:155], v[176:179], v[118:121]
	v_mfma_f32_16x16x32_bf16 v[110:113], v[140:143], v[184:187], v[110:113]
	v_mfma_f32_16x16x32_bf16 v[102:105], v[152:155], v[184:187], v[102:105]
	v_mfma_f32_16x16x32_bf16 v[94:97], v[140:143], v[204:207], v[94:97]
	v_mfma_f32_16x16x32_bf16 v[90:93], v[152:155], v[204:207], v[90:93]
	v_mfma_f32_16x16x32_bf16 v[78:81], v[140:143], v[212:215], v[78:81]
	v_mfma_f32_16x16x32_bf16 v[74:77], v[152:155], v[212:215], v[74:77]
	v_mfma_f32_16x16x32_bf16 v[126:129], v[148:151], v[180:183], v[126:129]
	v_mfma_f32_16x16x32_bf16 v[118:121], v[156:159], v[180:183], v[118:121]
	v_mfma_f32_16x16x32_bf16 v[110:113], v[148:151], v[188:191], v[110:113]
	v_mfma_f32_16x16x32_bf16 v[102:105], v[156:159], v[188:191], v[102:105]
	v_mfma_f32_16x16x32_bf16 v[94:97], v[148:151], v[208:211], v[94:97]
	v_mfma_f32_16x16x32_bf16 v[90:93], v[156:159], v[208:211], v[90:93]
	v_mfma_f32_16x16x32_bf16 v[78:81], v[148:151], v[216:219], v[78:81]
	v_mfma_f32_16x16x32_bf16 v[74:77], v[156:159], v[216:219], v[74:77]
	s_setprio 0
	s_setprio 1
	v_mfma_f32_16x16x32_bf16 v[122:125], v[160:163], v[176:179], v[122:125]
	v_mfma_f32_16x16x32_bf16 v[114:117], v[168:171], v[176:179], v[114:117]
	v_mfma_f32_16x16x32_bf16 v[106:109], v[160:163], v[184:187], v[106:109]
	v_mfma_f32_16x16x32_bf16 v[98:101], v[168:171], v[184:187], v[98:101]
	v_mfma_f32_16x16x32_bf16 v[86:89], v[160:163], v[204:207], v[86:89]
	v_mfma_f32_16x16x32_bf16 v[82:85], v[168:171], v[204:207], v[82:85]
	v_mfma_f32_16x16x32_bf16 v[70:73], v[160:163], v[212:215], v[70:73]
	v_mfma_f32_16x16x32_bf16 v[66:69], v[168:171], v[212:215], v[66:69]
	v_mfma_f32_16x16x32_bf16 v[122:125], v[164:167], v[180:183], v[122:125]
	v_mfma_f32_16x16x32_bf16 v[114:117], v[172:175], v[180:183], v[114:117]
	v_mfma_f32_16x16x32_bf16 v[106:109], v[164:167], v[188:191], v[106:109]
	v_mfma_f32_16x16x32_bf16 v[98:101], v[172:175], v[188:191], v[98:101]
	v_mfma_f32_16x16x32_bf16 v[86:89], v[164:167], v[208:211], v[86:89]
	v_mfma_f32_16x16x32_bf16 v[82:85], v[172:175], v[208:211], v[82:85]
	v_mfma_f32_16x16x32_bf16 v[70:73], v[164:167], v[216:219], v[70:73]
	v_mfma_f32_16x16x32_bf16 v[66:69], v[172:175], v[216:219], v[66:69]
	s_setprio 0
	s_barrier
; #define PG8_STAGE(bufoff, gbase, voff) do { _Pragma("unroll") for (int _i = 0; _i < 2; ++_i) \
;         __builtin_amdgcn_global_load_lds((const unsigned*)((const char*)(gbase) + (voff)[_i]), (PG8_LAS unsigned*)(lds + (bufoff) + ldsw + _i * 8192), 16, 0, 0); } while (0)
; #define PG8_LDA(dst, b, h) do { _Pragma("unroll") for (int m = 0; m < 4; ++m) _Pragma("unroll") for (int k = 0; k < 2; ++k) dst[m][k] = *(const PG8_LAS bf16x8*)(lds + PG8_SA(b, h) + aoff + m * 2048 + k * 1024); } while (0)
; #define PG8_MMA(ai, bj, At, Bt) do { __builtin_amdgcn_s_setprio(1); _Pragma("unroll") for (int m = 0; m < 4; ++m) _Pragma("unroll") for (int n = 0; n < 2; ++n) _Pragma("unroll") for (int k = 0; k < 2; ++k) \
;         acc[ai][bj][m][n] = __builtin_amdgcn_mfma_f32_16x16x32_bf16(Bt[n][k], At[m][k], acc[ai][bj][m][n], 0, 0, 0); __builtin_amdgcn_s_setprio(0); } while (0)
; #define PG8_WAIT_V(n) asm volatile("s_waitcnt vmcnt(" #n ")" ::: "memory")
; #define PG8_WAIT_L(n) asm volatile("s_waitcnt lgkmcnt(" #n ")" ::: "memory")
; #define PG8_BAR __builtin_amdgcn_s_barrier()
; #define PG8_SCHED __builtin_amdgcn_sched_barrier(0)
; template <class Epi, class Sched, bool ALIGN_EPI = false, bool SP2 = false>
; __device__ __forceinline__ void gemm_phase(PG8_LAS unsigned char* lds, const Gemm g, const Sched& S, const Epi& E, int tid_in) {
;     ...
;             PG8_LDA(At, 1, 1); PG8_STAGE(PG8_SB(1, 0), b3, voffB); PG8_STAGE(PG8_SB(1, 1), b3 + hstep, voffB); PG8_STAGE(PG8_SA(1, 0), a3, voffA);
;             PG8_WAIT_V(8); PG8_WAIT_L(0); PG8_BAR; PG8_MMA(1, 0, At, B0); PG8_MMA(1, 1, At, B1); PG8_BAR; PG8_SCHED;
;     ...
;         if constexpr (ALIGN_EPI) { if (wr == 0) PG8_BAR; }
	s_add_i32 s22, s45, s28
	v_lshl_add_u64 v[192:193], v[192:193], 0, s[84:85]
	s_mov_b32 m0, s22
	ds_read_b128 v[176:179], v147 offset:49152
	ds_read_b128 v[180:183], v147 offset:50176
	ds_read_b128 v[184:187], v147 offset:51200
	ds_read_b128 v[188:191], v147 offset:52224
	ds_read_b128 v[204:207], v147 offset:53248
	ds_read_b128 v[208:211], v147 offset:54272
	ds_read_b128 v[212:215], v147 offset:55296
	ds_read_b128 v[216:219], v147 offset:56320
	global_load_lds_dwordx4 v[192:193], off
	s_add_i32 m0, s22, 0x2000
	s_add_u32 s20, s20, 0x40080
	v_lshl_add_u64 v[192:193], v[220:221], 0, s[84:85]
	s_addc_u32 s21, s21, 0
	s_add_i32 s22, s46, s28
	global_load_lds_dwordx4 v[192:193], off
	v_lshl_add_u64 v[192:193], s[20:21], 0, v[32:33]
	s_mov_b32 m0, s22
	s_nop 0
	global_load_lds_dwordx4 v[192:193], off
	v_lshl_add_u64 v[192:193], s[20:21], 0, v[130:131]
	s_add_i32 m0, s22, 0x2000
	s_nop 0
	global_load_lds_dwordx4 v[192:193], off
	v_lshl_add_u64 v[192:193], v[222:223], 0, s[84:85]
	s_mov_b32 m0, s35
	s_nop 0
	global_load_lds_dwordx4 v[192:193], off
	v_lshl_add_u64 v[192:193], v[224:225], 0, s[84:85]
	s_mov_b32 m0, s36
	s_nop 0
	global_load_lds_dwordx4 v[192:193], off
	s_waitcnt vmcnt(8)
	s_waitcnt lgkmcnt(0)
	s_barrier
	s_setprio 1
	s_waitcnt lgkmcnt(0)
	v_mfma_f32_16x16x32_bf16 v[62:65], v[140:143], v[176:179], v[62:65]
	v_mfma_f32_16x16x32_bf16 v[58:61], v[152:155], v[176:179], v[58:61]
	v_mfma_f32_16x16x32_bf16 v[46:49], v[140:143], v[184:187], v[46:49]
	v_mfma_f32_16x16x32_bf16 v[42:45], v[152:155], v[184:187], v[42:45]
	v_mfma_f32_16x16x32_bf16 v[28:31], v[140:143], v[204:207], v[28:31]
	v_mfma_f32_16x16x32_bf16 v[24:27], v[152:155], v[204:207], v[24:27]
	v_mfma_f32_16x16x32_bf16 v[12:15], v[140:143], v[212:215], v[12:15]
	v_mfma_f32_16x16x32_bf16 v[8:11], v[152:155], v[212:215], v[8:11]
	v_mfma_f32_16x16x32_bf16 v[62:65], v[148:151], v[180:183], v[62:65]
	v_mfma_f32_16x16x32_bf16 v[58:61], v[156:159], v[180:183], v[58:61]
	v_mfma_f32_16x16x32_bf16 v[46:49], v[148:151], v[188:191], v[46:49]
	v_mfma_f32_16x16x32_bf16 v[42:45], v[156:159], v[188:191], v[42:45]
	v_mfma_f32_16x16x32_bf16 v[28:31], v[148:151], v[208:211], v[28:31]
	v_mfma_f32_16x16x32_bf16 v[24:27], v[156:159], v[208:211], v[24:27]
	v_mfma_f32_16x16x32_bf16 v[12:15], v[148:151], v[216:219], v[12:15]
	v_mfma_f32_16x16x32_bf16 v[8:11], v[156:159], v[216:219], v[8:11]
	s_setprio 0
	s_setprio 1
	v_mfma_f32_16x16x32_bf16 v[54:57], v[160:163], v[176:179], v[54:57]
	v_mfma_f32_16x16x32_bf16 v[50:53], v[168:171], v[176:179], v[50:53]
	v_mfma_f32_16x16x32_bf16 v[38:41], v[160:163], v[184:187], v[38:41]
	v_mfma_f32_16x16x32_bf16 v[34:37], v[168:171], v[184:187], v[34:37]
	v_mfma_f32_16x16x32_bf16 v[20:23], v[160:163], v[204:207], v[20:23]
	v_mfma_f32_16x16x32_bf16 v[16:19], v[168:171], v[204:207], v[16:19]
	v_mfma_f32_16x16x32_bf16 v[4:7], v[160:163], v[212:215], v[4:7]
	v_mfma_f32_16x16x32_bf16 v[0:3], v[168:171], v[212:215], v[0:3]
	v_mfma_f32_16x16x32_bf16 v[54:57], v[164:167], v[180:183], v[54:57]
	v_mfma_f32_16x16x32_bf16 v[50:53], v[172:175], v[180:183], v[50:53]
	v_mfma_f32_16x16x32_bf16 v[38:41], v[164:167], v[188:191], v[38:41]
	v_mfma_f32_16x16x32_bf16 v[34:37], v[172:175], v[188:191], v[34:37]
	v_mfma_f32_16x16x32_bf16 v[20:23], v[164:167], v[208:211], v[20:23]
	v_mfma_f32_16x16x32_bf16 v[16:19], v[172:175], v[208:211], v[16:19]
	v_mfma_f32_16x16x32_bf16 v[4:7], v[164:167], v[216:219], v[4:7]
	v_mfma_f32_16x16x32_bf16 v[0:3], v[172:175], v[216:219], v[0:3]
	s_setprio 0
	s_barrier
	s_add_i32 s44, s44, 2
	s_add_u32 s2, s2, 0x100
	s_addc_u32 s3, s3, 0
	s_add_u32 s42, s42, 0x100
	s_addc_u32 s43, s43, 0
	s_cmp_gt_u32 s44, 13
	s_cbranch_scc0 .LBB0_296
	s_and_b64 vcc, exec, s[10:11]
	s_cbranch_vccz .LBB0_299
	s_barrier
.LBB0_299:
	s_cmp_eq_u64 s[10:11], 0
	s_cbranch_scc0 .Lge_np0
	s_setprio 1

; #define PG8_STAGE(bufoff, gbase, voff) do { _Pragma("unroll") for (int _i = 0; _i < 2; ++_i) \
;         __builtin_amdgcn_global_load_lds((const unsigned*)((const char*)(gbase) + (voff)[_i]), (PG8_LAS unsigned*)(lds + (bufoff) + ldsw + _i * 8192), 16, 0, 0); } while (0)
; #define PG8_LDA(dst, b, h) do { _Pragma("unroll") for (int m = 0; m < 4; ++m) _Pragma("unroll") for (int k = 0; k < 2; ++k) dst[m][k] = *(const PG8_LAS bf16x8*)(lds + PG8_SA(b, h) + aoff + m * 2048 + k * 1024); } while (0)
; #define PG8_LDB(dst, b, h) do { _Pragma("unroll") for (int n = 0; n < 2; ++n) _Pragma("unroll") for (int k = 0; k < 2; ++k) dst[n][k] = *(const PG8_LAS bf16x8*)(lds + PG8_SB(b, h) + boff + n * 2048 + k * 1024); } while (0)
; #define PG8_MMA(ai, bj, At, Bt) do { __builtin_amdgcn_s_setprio(1); _Pragma("unroll") for (int m = 0; m < 4; ++m) _Pragma("unroll") for (int n = 0; n < 2; ++n) _Pragma("unroll") for (int k = 0; k < 2; ++k) \
;         acc[ai][bj][m][n] = __builtin_amdgcn_mfma_f32_16x16x32_bf16(Bt[n][k], At[m][k], acc[ai][bj][m][n], 0, 0, 0); __builtin_amdgcn_s_setprio(0); } while (0)
; #define PG8_WAIT_V(n) asm volatile("s_waitcnt vmcnt(" #n ")" ::: "memory")
; #define PG8_WAIT_L(n) asm volatile("s_waitcnt lgkmcnt(" #n ")" ::: "memory")
; template <class Epi, class Sched, bool ALIGN_EPI = false, bool SP2 = false>
; __device__ __forceinline__ void gemm_phase(PG8_LAS unsigned char* lds, const Gemm g, const Sched& S, const Epi& E, int tid_in) {
;     ...
;             const bool last = (t == nt - 2);
;             const char* a1 = cA + (size_t)(t + 1) * kstep;
;             const char* a2 = last ? nA : cA + (size_t)(t + 2) * kstep; const char* b2 = last ? nB : cB + (size_t)(t + 2) * kstep;
;             const char* a3 = a2 + kstep; const char* b3 = b2 + kstep;
;             if (last && has_next) S.a_ready(nxt);
;             if constexpr (SP2) {
;             PG8_LDB(B0, 0, 0); PG8_LDB(B1, 0, 1); PG8_SCHED; PG8_LDA(At, 0, 0); PG8_STAGE(PG8_SA(1, 1), a1 + hstep, voffA);
;             PG8_WAIT_V(8); PG8_WAIT_L(0); PG8_BAR; PG8_MMA(0, 0, At, B0); PG8_MMA(0, 1, At, B1); PG8_BAR; PG8_SCHED;
;             PG8_LDA(At, 0, 1); PG8_STAGE(PG8_SB(0, 0), b2, voffB); PG8_STAGE(PG8_SB(0, 1), b2 + hstep, voffB); PG8_STAGE(PG8_SA(0, 0), a2, voffA);
;             PG8_WAIT_V(8); PG8_WAIT_L(0); PG8_BAR; PG8_MMA(1, 0, At, B0); PG8_MMA(1, 1, At, B1); PG8_BAR; PG8_SCHED;
.LBB0_340:
	s_setprio 0
	s_add_u32 s24, s2, 0x100
	s_addc_u32 s25, s3, 0
	s_add_i32 s51, 0, 0x10000
	s_cmp_eq_u32 s50, 40
	s_cselect_b32 s29, s9, s25
	s_cselect_b32 s28, s8, s24
	s_cselect_b32 s27, s23, s49
	s_cselect_b32 s26, s22, s48
	s_add_i32 s53, 0, 0x14000
	v_add_u32_e32 v142, s51, v211
	v_add_u32_e32 v158, s53, v211
	ds_read_b128 v[130:133], v142
	ds_read_b128 v[134:137], v142 offset:1024
	ds_read_b128 v[138:141], v142 offset:2048
	ds_read_b128 v[142:145], v142 offset:3072
	ds_read_b128 v[146:149], v158
	ds_read_b128 v[150:153], v158 offset:1024
	ds_read_b128 v[154:157], v158 offset:2048
	ds_read_b128 v[158:161], v158 offset:3072
	v_lshl_add_u64 v[192:193], s[2:3], 0, v[184:185]
	s_add_i32 m0, s37, 0xc000
	ds_read_b128 v[162:165], v213
	ds_read_b128 v[166:169], v213 offset:1024
	ds_read_b128 v[170:173], v213 offset:2048
	ds_read_b128 v[174:177], v213 offset:3072
	ds_read_b128 v[188:191], v213 offset:4096
	ds_read_b128 v[204:207], v213 offset:5120
	ds_read_b128 v[214:217], v213 offset:6144
	ds_read_b128 v[218:221], v213 offset:7168
	global_load_lds_dwordx4 v[192:193], off
	v_lshl_add_u64 v[192:193], s[2:3], 0, v[186:187]
	s_add_i32 m0, s37, 0xe000
	s_nop 0
	global_load_lds_dwordx4 v[192:193], off
	s_waitcnt vmcnt(8)
	s_waitcnt lgkmcnt(0)
	s_barrier
	s_setprio 1
	s_waitcnt lgkmcnt(0)
	v_mfma_f32_16x16x32_bf16 v[126:129], v[130:133], v[162:165], v[126:129]
	v_mfma_f32_16x16x32_bf16 v[122:125], v[138:141], v[162:165], v[122:125]
	v_mfma_f32_16x16x32_bf16 v[110:113], v[130:133], v[170:173], v[110:113]
	v_mfma_f32_16x16x32_bf16 v[106:109], v[138:141], v[170:173], v[106:109]
	v_mfma_f32_16x16x32_bf16 v[94:97], v[130:133], v[188:191], v[94:97]
	v_mfma_f32_16x16x32_bf16 v[90:93], v[138:141], v[188:191], v[90:93]
	v_mfma_f32_16x16x32_bf16 v[78:81], v[130:133], v[214:217], v[78:81]
	v_mfma_f32_16x16x32_bf16 v[74:77], v[138:141], v[214:217], v[74:77]
	v_mfma_f32_16x16x32_bf16 v[126:129], v[134:137], v[166:169], v[126:129]
	v_mfma_f32_16x16x32_bf16 v[122:125], v[142:145], v[166:169], v[122:125]
	v_mfma_f32_16x16x32_bf16 v[110:113], v[134:137], v[174:177], v[110:113]
	v_mfma_f32_16x16x32_bf16 v[106:109], v[142:145], v[174:177], v[106:109]
	v_mfma_f32_16x16x32_bf16 v[94:97], v[134:137], v[204:207], v[94:97]
	v_mfma_f32_16x16x32_bf16 v[90:93], v[142:145], v[204:207], v[90:93]
	v_mfma_f32_16x16x32_bf16 v[78:81], v[134:137], v[218:221], v[78:81]
	v_mfma_f32_16x16x32_bf16 v[74:77], v[142:145], v[218:221], v[74:77]
	s_setprio 0
	s_setprio 1
	v_mfma_f32_16x16x32_bf16 v[118:121], v[146:149], v[162:165], v[118:121]
	v_mfma_f32_16x16x32_bf16 v[114:117], v[154:157], v[162:165], v[114:117]
	v_mfma_f32_16x16x32_bf16 v[102:105], v[146:149], v[170:173], v[102:105]
	v_mfma_f32_16x16x32_bf16 v[98:101], v[154:157], v[170:173], v[98:101]
	v_mfma_f32_16x16x32_bf16 v[86:89], v[146:149], v[188:191], v[86:89]
	v_mfma_f32_16x16x32_bf16 v[82:85], v[154:157], v[188:191], v[82:85]
	v_mfma_f32_16x16x32_bf16 v[70:73], v[146:149], v[214:217], v[70:73]
	v_mfma_f32_16x16x32_bf16 v[66:69], v[154:157], v[214:217], v[66:69]
	v_mfma_f32_16x16x32_bf16 v[118:121], v[150:153], v[166:169], v[118:121]
	v_mfma_f32_16x16x32_bf16 v[114:117], v[158:161], v[166:169], v[114:117]
	v_mfma_f32_16x16x32_bf16 v[102:105], v[150:153], v[174:177], v[102:105]
	v_mfma_f32_16x16x32_bf16 v[98:101], v[158:161], v[174:177], v[98:101]
	v_mfma_f32_16x16x32_bf16 v[86:89], v[150:153], v[204:207], v[86:89]
	v_mfma_f32_16x16x32_bf16 v[82:85], v[158:161], v[204:207], v[82:85]
	v_mfma_f32_16x16x32_bf16 v[70:73], v[150:153], v[218:221], v[70:73]
	v_mfma_f32_16x16x32_bf16 v[66:69], v[158:161], v[218:221], v[66:69]
	s_setprio 0
	s_barrier
	s_add_i32 s2, s51, s36
	v_lshl_add_u64 v[192:193], s[26:27], 0, v[32:33]
	s_mov_b32 m0, s2
	ds_read_b128 v[162:165], v213 offset:16384
	ds_read_b128 v[166:169], v213 offset:17408
	ds_read_b128 v[170:173], v213 offset:18432
	ds_read_b128 v[174:177], v213 offset:19456
	ds_read_b128 v[188:191], v213 offset:20480
	ds_read_b128 v[204:207], v213 offset:21504
	ds_read_b128 v[214:217], v213 offset:22528
	ds_read_b128 v[218:221], v213 offset:23552
	global_load_lds_dwordx4 v[192:193], off
	s_add_i32 m0, s2, 0x2000
	s_add_u32 s2, s26, 0xb0000
	v_lshl_add_u64 v[208:209], s[26:27], 0, v[178:179]
	s_addc_u32 s3, s27, 0
	s_add_i32 s51, s53, s36
	global_load_lds_dwordx4 v[208:209], off
	v_lshl_add_u64 v[222:223], s[2:3], 0, v[32:33]
	s_mov_b32 m0, s51
	v_lshl_add_u64 v[224:225], s[28:29], 0, v[180:181]
	global_load_lds_dwordx4 v[222:223], off
	v_lshl_add_u64 v[222:223], s[2:3], 0, v[178:179]
	s_add_i32 m0, s51, 0x2000
	s_nop 0
	global_load_lds_dwordx4 v[222:223], off
	v_lshl_add_u64 v[222:223], s[28:29], 0, v[182:183]
	s_mov_b32 m0, s37
	s_nop 0
	global_load_lds_dwordx4 v[222:223], off
	s_mov_b32 m0, s38
	s_nop 0
	global_load_lds_dwordx4 v[224:225], off
	s_waitcnt vmcnt(8)
	s_waitcnt lgkmcnt(0)
	s_barrier
; #define PG8_STAGE(bufoff, gbase, voff) do { _Pragma("unroll") for (int _i = 0; _i < 2; ++_i) \
;         __builtin_amdgcn_global_load_lds((const unsigned*)((const char*)(gbase) + (voff)[_i]), (PG8_LAS unsigned*)(lds + (bufoff) + ldsw + _i * 8192), 16, 0, 0); } while (0)
; #define PG8_LDA(dst, b, h) do { _Pragma("unroll") for (int m = 0; m < 4; ++m) _Pragma("unroll") for (int k = 0; k < 2; ++k) dst[m][k] = *(const PG8_LAS bf16x8*)(lds + PG8_SA(b, h) + aoff + m * 2048 + k * 1024); } while (0)
; #define PG8_LDB(dst, b, h) do { _Pragma("unroll") for (int n = 0; n < 2; ++n) _Pragma("unroll") for (int k = 0; k < 2; ++k) dst[n][k] = *(const PG8_LAS bf16x8*)(lds + PG8_SB(b, h) + boff + n * 2048 + k * 1024); } while (0)
; #define PG8_MMA(ai, bj, At, Bt) do { __builtin_amdgcn_s_setprio(1); _Pragma("unroll") for (int m = 0; m < 4; ++m) _Pragma("unroll") for (int n = 0; n < 2; ++n) _Pragma("unroll") for (int k = 0; k < 2; ++k) \
;         acc[ai][bj][m][n] = __builtin_amdgcn_mfma_f32_16x16x32_bf16(Bt[n][k], At[m][k], acc[ai][bj][m][n], 0, 0, 0); __builtin_amdgcn_s_setprio(0); } while (0)
; #define PG8_WAIT_V(n) asm volatile("s_waitcnt vmcnt(" #n ")" ::: "memory")
; #define PG8_WAIT_L(n) asm volatile("s_waitcnt lgkmcnt(" #n ")" ::: "memory")
; #define PG8_BAR __builtin_amdgcn_s_barrier()
; #define PG8_SCHED __builtin_amdgcn_sched_barrier(0)
; template <class Epi, class Sched, bool ALIGN_EPI = false, bool SP2 = false>
; __device__ __forceinline__ void gemm_phase(PG8_LAS unsigned char* lds, const Gemm g, const Sched& S, const Epi& E, int tid_in) {
;     ...
;             PG8_WAIT_V(8); PG8_WAIT_L(0); PG8_BAR; PG8_MMA(1, 0, At, B0); PG8_MMA(1, 1, At, B1); PG8_BAR; PG8_SCHED;
;             PG8_LDB(B0, 1, 0); PG8_LDB(B1, 1, 1); PG8_SCHED; PG8_LDA(At, 1, 0); PG8_STAGE(PG8_SA(0, 1), a2 + hstep, voffA);
;             PG8_WAIT_V(8); PG8_WAIT_L(0); PG8_BAR; PG8_MMA(0, 0, At, B0); PG8_MMA(0, 1, At, B1); PG8_BAR; PG8_SCHED;
	s_setprio 1
	s_waitcnt lgkmcnt(0)
	v_mfma_f32_16x16x32_bf16 v[62:65], v[130:133], v[162:165], v[62:65]
	v_mfma_f32_16x16x32_bf16 v[58:61], v[138:141], v[162:165], v[58:61]
	v_mfma_f32_16x16x32_bf16 v[46:49], v[130:133], v[170:173], v[46:49]
	v_mfma_f32_16x16x32_bf16 v[42:45], v[138:141], v[170:173], v[42:45]
	v_mfma_f32_16x16x32_bf16 v[28:31], v[130:133], v[188:191], v[28:31]
	v_mfma_f32_16x16x32_bf16 v[24:27], v[138:141], v[188:191], v[24:27]
	v_mfma_f32_16x16x32_bf16 v[12:15], v[130:133], v[214:217], v[12:15]
	v_mfma_f32_16x16x32_bf16 v[8:11], v[138:141], v[214:217], v[8:11]
	v_mfma_f32_16x16x32_bf16 v[62:65], v[134:137], v[166:169], v[62:65]
	v_mfma_f32_16x16x32_bf16 v[58:61], v[142:145], v[166:169], v[58:61]
	v_mfma_f32_16x16x32_bf16 v[46:49], v[134:137], v[174:177], v[46:49]
	v_mfma_f32_16x16x32_bf16 v[42:45], v[142:145], v[174:177], v[42:45]
	v_mfma_f32_16x16x32_bf16 v[28:31], v[134:137], v[204:207], v[28:31]
	v_mfma_f32_16x16x32_bf16 v[24:27], v[142:145], v[204:207], v[24:27]
	v_mfma_f32_16x16x32_bf16 v[12:15], v[134:137], v[218:221], v[12:15]
	v_mfma_f32_16x16x32_bf16 v[8:11], v[142:145], v[218:221], v[8:11]
	s_setprio 0
	s_setprio 1
	v_mfma_f32_16x16x32_bf16 v[54:57], v[146:149], v[162:165], v[54:57]
	v_mfma_f32_16x16x32_bf16 v[50:53], v[154:157], v[162:165], v[50:53]
	v_mfma_f32_16x16x32_bf16 v[38:41], v[146:149], v[170:173], v[38:41]
	v_mfma_f32_16x16x32_bf16 v[34:37], v[154:157], v[170:173], v[34:37]
	v_mfma_f32_16x16x32_bf16 v[20:23], v[146:149], v[188:191], v[20:23]
	v_mfma_f32_16x16x32_bf16 v[16:19], v[154:157], v[188:191], v[16:19]
	v_mfma_f32_16x16x32_bf16 v[4:7], v[146:149], v[214:217], v[4:7]
	v_mfma_f32_16x16x32_bf16 v[0:3], v[154:157], v[214:217], v[0:3]
	v_mfma_f32_16x16x32_bf16 v[54:57], v[150:153], v[166:169], v[54:57]
	v_mfma_f32_16x16x32_bf16 v[50:53], v[158:161], v[166:169], v[50:53]
	v_mfma_f32_16x16x32_bf16 v[38:41], v[150:153], v[174:177], v[38:41]
	v_mfma_f32_16x16x32_bf16 v[34:37], v[158:161], v[174:177], v[34:37]
	v_mfma_f32_16x16x32_bf16 v[20:23], v[150:153], v[204:207], v[20:23]
	v_mfma_f32_16x16x32_bf16 v[16:19], v[158:161], v[204:207], v[16:19]
	v_mfma_f32_16x16x32_bf16 v[4:7], v[150:153], v[218:221], v[4:7]
	v_mfma_f32_16x16x32_bf16 v[0:3], v[158:161], v[218:221], v[0:3]
	s_setprio 0
	s_barrier
	s_add_i32 s51, 0, 0x18000
	s_add_i32 s53, 0, 0x1c000
	v_add_u32_e32 v142, s51, v211
	v_add_u32_e32 v158, s53, v211
	ds_read_b128 v[130:133], v142
	ds_read_b128 v[134:137], v142 offset:1024
	ds_read_b128 v[138:141], v142 offset:2048
	ds_read_b128 v[142:145], v142 offset:3072
	ds_read_b128 v[146:149], v158
	ds_read_b128 v[150:153], v158 offset:1024
	ds_read_b128 v[154:157], v158 offset:2048
	ds_read_b128 v[158:161], v158 offset:3072
	s_add_u32 s2, s28, 0xb0000
	s_addc_u32 s3, s29, 0
	s_mov_b32 m0, s39
	v_lshl_add_u64 v[226:227], s[2:3], 0, v[182:183]
	ds_read_b128 v[162:165], v213 offset:32768
	ds_read_b128 v[166:169], v213 offset:33792
	ds_read_b128 v[170:173], v213 offset:34816
	ds_read_b128 v[174:177], v213 offset:35840
	ds_read_b128 v[188:191], v213 offset:36864
	ds_read_b128 v[204:207], v213 offset:37888
	ds_read_b128 v[214:217], v213 offset:38912
	ds_read_b128 v[218:221], v213 offset:39936
	global_load_lds_dwordx4 v[226:227], off
	v_lshl_add_u64 v[226:227], s[2:3], 0, v[180:181]
	s_mov_b32 m0, s40
	s_nop 0
	global_load_lds_dwordx4 v[226:227], off
	s_waitcnt vmcnt(8)
	s_waitcnt lgkmcnt(0)
	s_barrier
	s_setprio 1
	s_waitcnt lgkmcnt(0)
	v_mfma_f32_16x16x32_bf16 v[126:129], v[130:133], v[162:165], v[126:129]
	v_mfma_f32_16x16x32_bf16 v[122:125], v[138:141], v[162:165], v[122:125]
	v_mfma_f32_16x16x32_bf16 v[110:113], v[130:133], v[170:173], v[110:113]
	v_mfma_f32_16x16x32_bf16 v[106:109], v[138:141], v[170:173], v[106:109]
	v_mfma_f32_16x16x32_bf16 v[94:97], v[130:133], v[188:191], v[94:97]
	v_mfma_f32_16x16x32_bf16 v[90:93], v[138:141], v[188:191], v[90:93]
	v_mfma_f32_16x16x32_bf16 v[78:81], v[130:133], v[214:217], v[78:81]
	v_mfma_f32_16x16x32_bf16 v[74:77], v[138:141], v[214:217], v[74:77]
	v_mfma_f32_16x16x32_bf16 v[126:129], v[134:137], v[166:169], v[126:129]
	v_mfma_f32_16x16x32_bf16 v[122:125], v[142:145], v[166:169], v[122:125]
	v_mfma_f32_16x16x32_bf16 v[110:113], v[134:137], v[174:177], v[110:113]
	v_mfma_f32_16x16x32_bf16 v[106:109], v[142:145], v[174:177], v[106:109]
	v_mfma_f32_16x16x32_bf16 v[94:97], v[134:137], v[204:207], v[94:97]
	v_mfma_f32_16x16x32_bf16 v[90:93], v[142:145], v[204:207], v[90:93]
	v_mfma_f32_16x16x32_bf16 v[78:81], v[134:137], v[218:221], v[78:81]
	v_mfma_f32_16x16x32_bf16 v[74:77], v[142:145], v[218:221], v[74:77]
	s_setprio 0
	s_setprio 1
	v_mfma_f32_16x16x32_bf16 v[118:121], v[146:149], v[162:165], v[118:121]
	v_mfma_f32_16x16x32_bf16 v[114:117], v[154:157], v[162:165], v[114:117]
	v_mfma_f32_16x16x32_bf16 v[102:105], v[146:149], v[170:173], v[102:105]
	v_mfma_f32_16x16x32_bf16 v[98:101], v[154:157], v[170:173], v[98:101]
	v_mfma_f32_16x16x32_bf16 v[86:89], v[146:149], v[188:191], v[86:89]
	v_mfma_f32_16x16x32_bf16 v[82:85], v[154:157], v[188:191], v[82:85]
	v_mfma_f32_16x16x32_bf16 v[70:73], v[146:149], v[214:217], v[70:73]
	v_mfma_f32_16x16x32_bf16 v[66:69], v[154:157], v[214:217], v[66:69]
	v_mfma_f32_16x16x32_bf16 v[118:121], v[150:153], v[166:169], v[118:121]
	v_mfma_f32_16x16x32_bf16 v[114:117], v[158:161], v[166:169], v[114:117]
	v_mfma_f32_16x16x32_bf16 v[102:105], v[150:153], v[174:177], v[102:105]
	v_mfma_f32_16x16x32_bf16 v[98:101], v[158:161], v[174:177], v[98:101]
	v_mfma_f32_16x16x32_bf16 v[86:89], v[150:153], v[204:207], v[86:89]
	v_mfma_f32_16x16x32_bf16 v[82:85], v[158:161], v[204:207], v[82:85]
	v_mfma_f32_16x16x32_bf16 v[70:73], v[150:153], v[218:221], v[70:73]
	v_mfma_f32_16x16x32_bf16 v[66:69], v[158:161], v[218:221], v[66:69]
	s_setprio 0
	s_barrier
; #define PG8_STAGE(bufoff, gbase, voff) do { _Pragma("unroll") for (int _i = 0; _i < 2; ++_i) \
;         __builtin_amdgcn_global_load_lds((const unsigned*)((const char*)(gbase) + (voff)[_i]), (PG8_LAS unsigned*)(lds + (bufoff) + ldsw + _i * 8192), 16, 0, 0); } while (0)
; #define PG8_LDA(dst, b, h) do { _Pragma("unroll") for (int m = 0; m < 4; ++m) _Pragma("unroll") for (int k = 0; k < 2; ++k) dst[m][k] = *(const PG8_LAS bf16x8*)(lds + PG8_SA(b, h) + aoff + m * 2048 + k * 1024); } while (0)
; #define PG8_MMA(ai, bj, At, Bt) do { __builtin_amdgcn_s_setprio(1); _Pragma("unroll") for (int m = 0; m < 4; ++m) _Pragma("unroll") for (int n = 0; n < 2; ++n) _Pragma("unroll") for (int k = 0; k < 2; ++k) \
;         acc[ai][bj][m][n] = __builtin_amdgcn_mfma_f32_16x16x32_bf16(Bt[n][k], At[m][k], acc[ai][bj][m][n], 0, 0, 0); __builtin_amdgcn_s_setprio(0); } while (0)
; #define PG8_WAIT_V(n) asm volatile("s_waitcnt vmcnt(" #n ")" ::: "memory")
; #define PG8_WAIT_L(n) asm volatile("s_waitcnt lgkmcnt(" #n ")" ::: "memory")
; #define PG8_BAR __builtin_amdgcn_s_barrier()
; #define PG8_SCHED __builtin_amdgcn_sched_barrier(0)
; template <class Epi, class Sched, bool ALIGN_EPI = false, bool SP2 = false>
; __device__ __forceinline__ void gemm_phase(PG8_LAS unsigned char* lds, const Gemm g, const Sched& S, const Epi& E, int tid_in) {
;     ...
;             PG8_LDA(At, 1, 1); PG8_STAGE(PG8_SB(1, 0), b3, voffB); PG8_STAGE(PG8_SB(1, 1), b3 + hstep, voffB); PG8_STAGE(PG8_SA(1, 0), a3, voffA);
;             PG8_WAIT_V(8); PG8_WAIT_L(0); PG8_BAR; PG8_MMA(1, 0, At, B0); PG8_MMA(1, 1, At, B1); PG8_BAR; PG8_SCHED;
;     ...
;         if constexpr (ALIGN_EPI) { if (wr == 0) PG8_BAR; }
	s_add_i32 s2, s51, s36
	v_lshl_add_u64 v[192:193], v[192:193], 0, s[84:85]
	s_mov_b32 m0, s2
	ds_read_b128 v[162:165], v213 offset:49152
	ds_read_b128 v[166:169], v213 offset:50176
	ds_read_b128 v[170:173], v213 offset:51200
	ds_read_b128 v[174:177], v213 offset:52224
	ds_read_b128 v[188:191], v213 offset:53248
	ds_read_b128 v[204:207], v213 offset:54272
	ds_read_b128 v[214:217], v213 offset:55296
	ds_read_b128 v[218:221], v213 offset:56320
	global_load_lds_dwordx4 v[192:193], off
	s_add_i32 m0, s2, 0x2000
	s_add_u32 s2, s26, 0xb0080
	v_lshl_add_u64 v[192:193], v[208:209], 0, s[84:85]
	s_addc_u32 s3, s27, 0
	s_add_i32 s26, s53, s36
	global_load_lds_dwordx4 v[192:193], off
	v_lshl_add_u64 v[192:193], s[2:3], 0, v[32:33]
	s_mov_b32 m0, s26
	s_nop 0
	global_load_lds_dwordx4 v[192:193], off
	v_lshl_add_u64 v[192:193], s[2:3], 0, v[178:179]
	s_add_i32 m0, s26, 0x2000
	s_nop 0
	global_load_lds_dwordx4 v[192:193], off
	v_lshl_add_u64 v[192:193], v[222:223], 0, s[84:85]
	s_mov_b32 m0, s41
	s_nop 0
	global_load_lds_dwordx4 v[192:193], off
	v_lshl_add_u64 v[192:193], v[224:225], 0, s[84:85]
	s_mov_b32 m0, s42
	s_nop 0
	global_load_lds_dwordx4 v[192:193], off
	s_waitcnt vmcnt(8)
	s_waitcnt lgkmcnt(0)
	s_barrier
	s_setprio 1
	s_waitcnt lgkmcnt(0)
	v_mfma_f32_16x16x32_bf16 v[62:65], v[130:133], v[162:165], v[62:65]
	v_mfma_f32_16x16x32_bf16 v[58:61], v[138:141], v[162:165], v[58:61]
	v_mfma_f32_16x16x32_bf16 v[46:49], v[130:133], v[170:173], v[46:49]
	v_mfma_f32_16x16x32_bf16 v[42:45], v[138:141], v[170:173], v[42:45]
	v_mfma_f32_16x16x32_bf16 v[28:31], v[130:133], v[188:191], v[28:31]
	v_mfma_f32_16x16x32_bf16 v[24:27], v[138:141], v[188:191], v[24:27]
	v_mfma_f32_16x16x32_bf16 v[12:15], v[130:133], v[214:217], v[12:15]
	v_mfma_f32_16x16x32_bf16 v[8:11], v[138:141], v[214:217], v[8:11]
	v_mfma_f32_16x16x32_bf16 v[62:65], v[134:137], v[166:169], v[62:65]
	v_mfma_f32_16x16x32_bf16 v[58:61], v[142:145], v[166:169], v[58:61]
	v_mfma_f32_16x16x32_bf16 v[46:49], v[134:137], v[174:177], v[46:49]
	v_mfma_f32_16x16x32_bf16 v[42:45], v[142:145], v[174:177], v[42:45]
	v_mfma_f32_16x16x32_bf16 v[28:31], v[134:137], v[204:207], v[28:31]
	v_mfma_f32_16x16x32_bf16 v[24:27], v[142:145], v[204:207], v[24:27]
	v_mfma_f32_16x16x32_bf16 v[12:15], v[134:137], v[218:221], v[12:15]
	v_mfma_f32_16x16x32_bf16 v[8:11], v[142:145], v[218:221], v[8:11]
	s_setprio 0
	s_setprio 1
	v_mfma_f32_16x16x32_bf16 v[54:57], v[146:149], v[162:165], v[54:57]
	v_mfma_f32_16x16x32_bf16 v[50:53], v[154:157], v[162:165], v[50:53]
	v_mfma_f32_16x16x32_bf16 v[38:41], v[146:149], v[170:173], v[38:41]
	v_mfma_f32_16x16x32_bf16 v[34:37], v[154:157], v[170:173], v[34:37]
	v_mfma_f32_16x16x32_bf16 v[20:23], v[146:149], v[188:191], v[20:23]
	v_mfma_f32_16x16x32_bf16 v[16:19], v[154:157], v[188:191], v[16:19]
	v_mfma_f32_16x16x32_bf16 v[4:7], v[146:149], v[214:217], v[4:7]
	v_mfma_f32_16x16x32_bf16 v[0:3], v[154:157], v[214:217], v[0:3]
	v_mfma_f32_16x16x32_bf16 v[54:57], v[150:153], v[166:169], v[54:57]
	v_mfma_f32_16x16x32_bf16 v[50:53], v[158:161], v[166:169], v[50:53]
	v_mfma_f32_16x16x32_bf16 v[38:41], v[150:153], v[174:177], v[38:41]
	v_mfma_f32_16x16x32_bf16 v[34:37], v[158:161], v[174:177], v[34:37]
	v_mfma_f32_16x16x32_bf16 v[20:23], v[150:153], v[204:207], v[20:23]
	v_mfma_f32_16x16x32_bf16 v[16:19], v[158:161], v[204:207], v[16:19]
	v_mfma_f32_16x16x32_bf16 v[4:7], v[150:153], v[218:221], v[4:7]
	v_mfma_f32_16x16x32_bf16 v[0:3], v[158:161], v[218:221], v[0:3]
	s_setprio 0
	s_barrier
	s_add_i32 s50, s50, 2
	s_add_u32 s48, s48, 0x100
	s_addc_u32 s49, s49, 0
	s_cmp_gt_u32 s50, 41
	s_mov_b64 s[2:3], s[24:25]
	s_cbranch_scc0 .LBB0_340
	s_and_b64 vcc, exec, s[20:21]
	s_cbranch_vccz .LBB0_343
	s_barrier
.LBB0_343:
	s_cmp_eq_u64 s[20:21], 0
	s_cbranch_scc0 .Lge_np1
	s_setprio 1

; #define PG8_STAGE(bufoff, gbase, voff) do { _Pragma("unroll") for (int _i = 0; _i < 2; ++_i) \
;         __builtin_amdgcn_global_load_lds((const unsigned*)((const char*)(gbase) + (voff)[_i]), (PG8_LAS unsigned*)(lds + (bufoff) + ldsw + _i * 8192), 16, 0, 0); } while (0)
; #define PG8_LDA(dst, b, h) do { _Pragma("unroll") for (int m = 0; m < 4; ++m) _Pragma("unroll") for (int k = 0; k < 2; ++k) dst[m][k] = *(const PG8_LAS bf16x8*)(lds + PG8_SA(b, h) + aoff + m * 2048 + k * 1024); } while (0)
; #define PG8_LDB(dst, b, h) do { _Pragma("unroll") for (int n = 0; n < 2; ++n) _Pragma("unroll") for (int k = 0; k < 2; ++k) dst[n][k] = *(const PG8_LAS bf16x8*)(lds + PG8_SB(b, h) + boff + n * 2048 + k * 1024); } while (0)
; #define PG8_MMA(ai, bj, At, Bt) do { __builtin_amdgcn_s_setprio(1); _Pragma("unroll") for (int m = 0; m < 4; ++m) _Pragma("unroll") for (int n = 0; n < 2; ++n) _Pragma("unroll") for (int k = 0; k < 2; ++k) \
;         acc[ai][bj][m][n] = __builtin_amdgcn_mfma_f32_16x16x32_bf16(Bt[n][k], At[m][k], acc[ai][bj][m][n], 0, 0, 0); __builtin_amdgcn_s_setprio(0); } while (0)
; #define PG8_WAIT_V(n) asm volatile("s_waitcnt vmcnt(" #n ")" ::: "memory")
; #define PG8_WAIT_L(n) asm volatile("s_waitcnt lgkmcnt(" #n ")" ::: "memory")
; template <class Epi, class Sched, bool ALIGN_EPI = false, bool SP2 = false>
; __device__ __forceinline__ void gemm_phase(PG8_LAS unsigned char* lds, const Gemm g, const Sched& S, const Epi& E, int tid_in) {
;     ...
;             const bool last = (t == nt - 2);
;             const char* a1 = cA + (size_t)(t + 1) * kstep;
;             const char* a2 = last ? nA : cA + (size_t)(t + 2) * kstep; const char* b2 = last ? nB : cB + (size_t)(t + 2) * kstep;
;             const char* a3 = a2 + kstep; const char* b3 = b2 + kstep;
;             if (last && has_next) S.a_ready(nxt);
;             if constexpr (SP2) {
;             PG8_LDB(B0, 0, 0); PG8_LDB(B1, 0, 1); PG8_SCHED; PG8_LDA(At, 0, 0); PG8_STAGE(PG8_SA(1, 1), a1 + hstep, voffA);
;             PG8_WAIT_V(8); PG8_WAIT_L(0); PG8_BAR; PG8_MMA(0, 0, At, B0); PG8_MMA(0, 1, At, B1); PG8_BAR; PG8_SCHED;
;             PG8_LDA(At, 0, 1); PG8_STAGE(PG8_SB(0, 0), b2, voffB); PG8_STAGE(PG8_SB(0, 1), b2 + hstep, voffB); PG8_STAGE(PG8_SA(0, 0), a2, voffA);
;             PG8_WAIT_V(8); PG8_WAIT_L(0); PG8_BAR; PG8_MMA(1, 0, At, B0); PG8_MMA(1, 1, At, B1); PG8_BAR; PG8_SCHED;
.LBB0_388:
	s_setprio 0
	s_add_u32 s20, s6, 0xfffc0080
	s_addc_u32 s21, s7, -1
	s_add_i32 s45, 0, 0x10000
	s_cmp_eq_u32 s44, 12
	s_cselect_b32 s23, s15, s21
	s_cselect_b32 s22, s40, s20
	s_cselect_b32 s21, s13, s43
	s_cselect_b32 s20, s41, s42
	s_add_i32 s48, 0, 0x14000
	v_add_u32_e32 v156, s45, v149
	v_add_u32_e32 v172, s48, v149
	ds_read_b128 v[140:143], v156
	ds_read_b128 v[144:147], v156 offset:1024
	ds_read_b128 v[152:155], v156 offset:2048
	ds_read_b128 v[156:159], v156 offset:3072
	ds_read_b128 v[160:163], v172
	ds_read_b128 v[164:167], v172 offset:1024
	ds_read_b128 v[168:171], v172 offset:2048
	ds_read_b128 v[172:175], v172 offset:3072
	v_lshl_add_u64 v[192:193], s[6:7], 0, v[136:137]
	s_add_i32 m0, s29, 0xc000
	ds_read_b128 v[176:179], v151
	ds_read_b128 v[180:183], v151 offset:1024
	ds_read_b128 v[184:187], v151 offset:2048
	ds_read_b128 v[188:191], v151 offset:3072
	ds_read_b128 v[204:207], v151 offset:4096
	ds_read_b128 v[208:211], v151 offset:5120
	ds_read_b128 v[212:215], v151 offset:6144
	ds_read_b128 v[216:219], v151 offset:7168
	global_load_lds_dwordx4 v[192:193], off
	v_lshl_add_u64 v[192:193], s[6:7], 0, v[138:139]
	s_add_i32 m0, s29, 0xe000
	s_nop 0
	global_load_lds_dwordx4 v[192:193], off
	s_waitcnt vmcnt(8)
	s_waitcnt lgkmcnt(0)
	s_barrier
	s_setprio 1
	s_waitcnt lgkmcnt(0)
	v_mfma_f32_16x16x32_bf16 v[126:129], v[140:143], v[176:179], v[126:129]
	v_mfma_f32_16x16x32_bf16 v[122:125], v[152:155], v[176:179], v[122:125]
	v_mfma_f32_16x16x32_bf16 v[110:113], v[140:143], v[184:187], v[110:113]
	v_mfma_f32_16x16x32_bf16 v[106:109], v[152:155], v[184:187], v[106:109]
	v_mfma_f32_16x16x32_bf16 v[94:97], v[140:143], v[204:207], v[94:97]
	v_mfma_f32_16x16x32_bf16 v[90:93], v[152:155], v[204:207], v[90:93]
	v_mfma_f32_16x16x32_bf16 v[78:81], v[140:143], v[212:215], v[78:81]
	v_mfma_f32_16x16x32_bf16 v[74:77], v[152:155], v[212:215], v[74:77]
	v_mfma_f32_16x16x32_bf16 v[126:129], v[144:147], v[180:183], v[126:129]
	v_mfma_f32_16x16x32_bf16 v[122:125], v[156:159], v[180:183], v[122:125]
	v_mfma_f32_16x16x32_bf16 v[110:113], v[144:147], v[188:191], v[110:113]
	v_mfma_f32_16x16x32_bf16 v[106:109], v[156:159], v[188:191], v[106:109]
	v_mfma_f32_16x16x32_bf16 v[94:97], v[144:147], v[208:211], v[94:97]
	v_mfma_f32_16x16x32_bf16 v[90:93], v[156:159], v[208:211], v[90:93]
	v_mfma_f32_16x16x32_bf16 v[78:81], v[144:147], v[216:219], v[78:81]
	v_mfma_f32_16x16x32_bf16 v[74:77], v[156:159], v[216:219], v[74:77]
	s_setprio 0
	s_setprio 1
	v_mfma_f32_16x16x32_bf16 v[118:121], v[160:163], v[176:179], v[118:121]
	v_mfma_f32_16x16x32_bf16 v[114:117], v[168:171], v[176:179], v[114:117]
	v_mfma_f32_16x16x32_bf16 v[102:105], v[160:163], v[184:187], v[102:105]
	v_mfma_f32_16x16x32_bf16 v[98:101], v[168:171], v[184:187], v[98:101]
	v_mfma_f32_16x16x32_bf16 v[86:89], v[160:163], v[204:207], v[86:89]
	v_mfma_f32_16x16x32_bf16 v[82:85], v[168:171], v[204:207], v[82:85]
	v_mfma_f32_16x16x32_bf16 v[70:73], v[160:163], v[212:215], v[70:73]
	v_mfma_f32_16x16x32_bf16 v[66:69], v[168:171], v[212:215], v[66:69]
	v_mfma_f32_16x16x32_bf16 v[118:121], v[164:167], v[180:183], v[118:121]
	v_mfma_f32_16x16x32_bf16 v[114:117], v[172:175], v[180:183], v[114:117]
	v_mfma_f32_16x16x32_bf16 v[102:105], v[164:167], v[188:191], v[102:105]
	v_mfma_f32_16x16x32_bf16 v[98:101], v[172:175], v[188:191], v[98:101]
	v_mfma_f32_16x16x32_bf16 v[86:89], v[164:167], v[208:211], v[86:89]
	v_mfma_f32_16x16x32_bf16 v[82:85], v[172:175], v[208:211], v[82:85]
	v_mfma_f32_16x16x32_bf16 v[70:73], v[164:167], v[216:219], v[70:73]
	v_mfma_f32_16x16x32_bf16 v[66:69], v[172:175], v[216:219], v[66:69]
	s_setprio 0
	s_barrier
	s_add_i32 s45, s45, s28
	v_lshl_add_u64 v[192:193], s[20:21], 0, v[32:33]
	s_mov_b32 m0, s45
	ds_read_b128 v[176:179], v151 offset:16384
	ds_read_b128 v[180:183], v151 offset:17408
	ds_read_b128 v[184:187], v151 offset:18432
	ds_read_b128 v[188:191], v151 offset:19456
	ds_read_b128 v[204:207], v151 offset:20480
	ds_read_b128 v[208:211], v151 offset:21504
	ds_read_b128 v[212:215], v151 offset:22528
	ds_read_b128 v[216:219], v151 offset:23552
	global_load_lds_dwordx4 v[192:193], off
	s_add_i32 m0, s45, 0x2000
	s_add_u32 s46, s20, 0x40000
	v_lshl_add_u64 v[220:221], s[20:21], 0, v[130:131]
	s_addc_u32 s47, s21, 0
	s_add_i32 s45, s48, s28
	global_load_lds_dwordx4 v[220:221], off
	v_lshl_add_u64 v[222:223], s[46:47], 0, v[32:33]
	s_mov_b32 m0, s45
	v_lshl_add_u64 v[224:225], s[22:23], 0, v[132:133]
	global_load_lds_dwordx4 v[222:223], off
	v_lshl_add_u64 v[222:223], s[46:47], 0, v[130:131]
	s_add_i32 m0, s45, 0x2000
	s_nop 0
	global_load_lds_dwordx4 v[222:223], off
	v_lshl_add_u64 v[222:223], s[22:23], 0, v[134:135]
	s_mov_b32 m0, s29
	s_nop 0
	global_load_lds_dwordx4 v[222:223], off
	s_mov_b32 m0, s30
	s_nop 0
	global_load_lds_dwordx4 v[224:225], off
	s_waitcnt vmcnt(8)
	s_waitcnt lgkmcnt(0)
	s_barrier
; #define PG8_STAGE(bufoff, gbase, voff) do { _Pragma("unroll") for (int _i = 0; _i < 2; ++_i) \
;         __builtin_amdgcn_global_load_lds((const unsigned*)((const char*)(gbase) + (voff)[_i]), (PG8_LAS unsigned*)(lds + (bufoff) + ldsw + _i * 8192), 16, 0, 0); } while (0)
; #define PG8_LDA(dst, b, h) do { _Pragma("unroll") for (int m = 0; m < 4; ++m) _Pragma("unroll") for (int k = 0; k < 2; ++k) dst[m][k] = *(const PG8_LAS bf16x8*)(lds + PG8_SA(b, h) + aoff + m * 2048 + k * 1024); } while (0)
; #define PG8_LDB(dst, b, h) do { _Pragma("unroll") for (int n = 0; n < 2; ++n) _Pragma("unroll") for (int k = 0; k < 2; ++k) dst[n][k] = *(const PG8_LAS bf16x8*)(lds + PG8_SB(b, h) + boff + n * 2048 + k * 1024); } while (0)
; #define PG8_MMA(ai, bj, At, Bt) do { __builtin_amdgcn_s_setprio(1); _Pragma("unroll") for (int m = 0; m < 4; ++m) _Pragma("unroll") for (int n = 0; n < 2; ++n) _Pragma("unroll") for (int k = 0; k < 2; ++k) \
;         acc[ai][bj][m][n] = __builtin_amdgcn_mfma_f32_16x16x32_bf16(Bt[n][k], At[m][k], acc[ai][bj][m][n], 0, 0, 0); __builtin_amdgcn_s_setprio(0); } while (0)
; #define PG8_WAIT_V(n) asm volatile("s_waitcnt vmcnt(" #n ")" ::: "memory")
; #define PG8_WAIT_L(n) asm volatile("s_waitcnt lgkmcnt(" #n ")" ::: "memory")
; #define PG8_BAR __builtin_amdgcn_s_barrier()
; #define PG8_SCHED __builtin_amdgcn_sched_barrier(0)
; template <class Epi, class Sched, bool ALIGN_EPI = false, bool SP2 = false>
; __device__ __forceinline__ void gemm_phase(PG8_LAS unsigned char* lds, const Gemm g, const Sched& S, const Epi& E, int tid_in) {
;     ...
;             PG8_WAIT_V(8); PG8_WAIT_L(0); PG8_BAR; PG8_MMA(1, 0, At, B0); PG8_MMA(1, 1, At, B1); PG8_BAR; PG8_SCHED;
;             PG8_LDB(B0, 1, 0); PG8_LDB(B1, 1, 1); PG8_SCHED; PG8_LDA(At, 1, 0); PG8_STAGE(PG8_SA(0, 1), a2 + hstep, voffA);
;             PG8_WAIT_V(8); PG8_WAIT_L(0); PG8_BAR; PG8_MMA(0, 0, At, B0); PG8_MMA(0, 1, At, B1); PG8_BAR; PG8_SCHED;
	s_setprio 1
	s_waitcnt lgkmcnt(0)
	v_mfma_f32_16x16x32_bf16 v[62:65], v[140:143], v[176:179], v[62:65]
	v_mfma_f32_16x16x32_bf16 v[58:61], v[152:155], v[176:179], v[58:61]
	v_mfma_f32_16x16x32_bf16 v[46:49], v[140:143], v[184:187], v[46:49]
	v_mfma_f32_16x16x32_bf16 v[42:45], v[152:155], v[184:187], v[42:45]
	v_mfma_f32_16x16x32_bf16 v[28:31], v[140:143], v[204:207], v[28:31]
	v_mfma_f32_16x16x32_bf16 v[24:27], v[152:155], v[204:207], v[24:27]
	v_mfma_f32_16x16x32_bf16 v[12:15], v[140:143], v[212:215], v[12:15]
	v_mfma_f32_16x16x32_bf16 v[8:11], v[152:155], v[212:215], v[8:11]
	v_mfma_f32_16x16x32_bf16 v[62:65], v[144:147], v[180:183], v[62:65]
	v_mfma_f32_16x16x32_bf16 v[58:61], v[156:159], v[180:183], v[58:61]
	v_mfma_f32_16x16x32_bf16 v[46:49], v[144:147], v[188:191], v[46:49]
	v_mfma_f32_16x16x32_bf16 v[42:45], v[156:159], v[188:191], v[42:45]
	v_mfma_f32_16x16x32_bf16 v[28:31], v[144:147], v[208:211], v[28:31]
	v_mfma_f32_16x16x32_bf16 v[24:27], v[156:159], v[208:211], v[24:27]
	v_mfma_f32_16x16x32_bf16 v[12:15], v[144:147], v[216:219], v[12:15]
	v_mfma_f32_16x16x32_bf16 v[8:11], v[156:159], v[216:219], v[8:11]
	s_setprio 0
	s_setprio 1
	v_mfma_f32_16x16x32_bf16 v[54:57], v[160:163], v[176:179], v[54:57]
	v_mfma_f32_16x16x32_bf16 v[50:53], v[168:171], v[176:179], v[50:53]
	v_mfma_f32_16x16x32_bf16 v[38:41], v[160:163], v[184:187], v[38:41]
	v_mfma_f32_16x16x32_bf16 v[34:37], v[168:171], v[184:187], v[34:37]
	v_mfma_f32_16x16x32_bf16 v[20:23], v[160:163], v[204:207], v[20:23]
	v_mfma_f32_16x16x32_bf16 v[16:19], v[168:171], v[204:207], v[16:19]
	v_mfma_f32_16x16x32_bf16 v[4:7], v[160:163], v[212:215], v[4:7]
	v_mfma_f32_16x16x32_bf16 v[0:3], v[168:171], v[212:215], v[0:3]
	v_mfma_f32_16x16x32_bf16 v[54:57], v[164:167], v[180:183], v[54:57]
	v_mfma_f32_16x16x32_bf16 v[50:53], v[172:175], v[180:183], v[50:53]
	v_mfma_f32_16x16x32_bf16 v[38:41], v[164:167], v[188:191], v[38:41]
	v_mfma_f32_16x16x32_bf16 v[34:37], v[172:175], v[188:191], v[34:37]
	v_mfma_f32_16x16x32_bf16 v[20:23], v[164:167], v[208:211], v[20:23]
	v_mfma_f32_16x16x32_bf16 v[16:19], v[172:175], v[208:211], v[16:19]
	v_mfma_f32_16x16x32_bf16 v[4:7], v[164:167], v[216:219], v[4:7]
	v_mfma_f32_16x16x32_bf16 v[0:3], v[172:175], v[216:219], v[0:3]
	s_setprio 0
	s_barrier
	s_add_i32 s45, 0, 0x18000
	s_add_i32 s46, 0, 0x1c000
	v_add_u32_e32 v156, s45, v149
	v_add_u32_e32 v172, s46, v149
	ds_read_b128 v[140:143], v156
	ds_read_b128 v[144:147], v156 offset:1024
	ds_read_b128 v[152:155], v156 offset:2048
	ds_read_b128 v[156:159], v156 offset:3072
	ds_read_b128 v[160:163], v172
	ds_read_b128 v[164:167], v172 offset:1024
	ds_read_b128 v[168:171], v172 offset:2048
	ds_read_b128 v[172:175], v172 offset:3072
	s_add_u32 s22, s22, 0x40000
	s_addc_u32 s23, s23, 0
	s_mov_b32 m0, s31
	v_lshl_add_u64 v[226:227], s[22:23], 0, v[134:135]
	ds_read_b128 v[176:179], v151 offset:32768
	ds_read_b128 v[180:183], v151 offset:33792
	ds_read_b128 v[184:187], v151 offset:34816
	ds_read_b128 v[188:191], v151 offset:35840
	ds_read_b128 v[204:207], v151 offset:36864
	ds_read_b128 v[208:211], v151 offset:37888
	ds_read_b128 v[212:215], v151 offset:38912
	ds_read_b128 v[216:219], v151 offset:39936
	global_load_lds_dwordx4 v[226:227], off
	v_lshl_add_u64 v[226:227], s[22:23], 0, v[132:133]
	s_mov_b32 m0, s34
	s_nop 0
	global_load_lds_dwordx4 v[226:227], off
	s_waitcnt vmcnt(8)
	s_waitcnt lgkmcnt(0)
	s_barrier
	s_setprio 1
	s_waitcnt lgkmcnt(0)
	v_mfma_f32_16x16x32_bf16 v[126:129], v[140:143], v[176:179], v[126:129]
	v_mfma_f32_16x16x32_bf16 v[122:125], v[152:155], v[176:179], v[122:125]
	v_mfma_f32_16x16x32_bf16 v[110:113], v[140:143], v[184:187], v[110:113]
	v_mfma_f32_16x16x32_bf16 v[106:109], v[152:155], v[184:187], v[106:109]
	v_mfma_f32_16x16x32_bf16 v[94:97], v[140:143], v[204:207], v[94:97]
	v_mfma_f32_16x16x32_bf16 v[90:93], v[152:155], v[204:207], v[90:93]
	v_mfma_f32_16x16x32_bf16 v[78:81], v[140:143], v[212:215], v[78:81]
	v_mfma_f32_16x16x32_bf16 v[74:77], v[152:155], v[212:215], v[74:77]
	v_mfma_f32_16x16x32_bf16 v[126:129], v[144:147], v[180:183], v[126:129]
	v_mfma_f32_16x16x32_bf16 v[122:125], v[156:159], v[180:183], v[122:125]
	v_mfma_f32_16x16x32_bf16 v[110:113], v[144:147], v[188:191], v[110:113]
	v_mfma_f32_16x16x32_bf16 v[106:109], v[156:159], v[188:191], v[106:109]
	v_mfma_f32_16x16x32_bf16 v[94:97], v[144:147], v[208:211], v[94:97]
	v_mfma_f32_16x16x32_bf16 v[90:93], v[156:159], v[208:211], v[90:93]
	v_mfma_f32_16x16x32_bf16 v[78:81], v[144:147], v[216:219], v[78:81]
	v_mfma_f32_16x16x32_bf16 v[74:77], v[156:159], v[216:219], v[74:77]
	s_setprio 0
	s_setprio 1
	v_mfma_f32_16x16x32_bf16 v[118:121], v[160:163], v[176:179], v[118:121]
	v_mfma_f32_16x16x32_bf16 v[114:117], v[168:171], v[176:179], v[114:117]
	v_mfma_f32_16x16x32_bf16 v[102:105], v[160:163], v[184:187], v[102:105]
	v_mfma_f32_16x16x32_bf16 v[98:101], v[168:171], v[184:187], v[98:101]
	v_mfma_f32_16x16x32_bf16 v[86:89], v[160:163], v[204:207], v[86:89]
	v_mfma_f32_16x16x32_bf16 v[82:85], v[168:171], v[204:207], v[82:85]
	v_mfma_f32_16x16x32_bf16 v[70:73], v[160:163], v[212:215], v[70:73]
	v_mfma_f32_16x16x32_bf16 v[66:69], v[168:171], v[212:215], v[66:69]
	v_mfma_f32_16x16x32_bf16 v[118:121], v[164:167], v[180:183], v[118:121]
	v_mfma_f32_16x16x32_bf16 v[114:117], v[172:175], v[180:183], v[114:117]
	v_mfma_f32_16x16x32_bf16 v[102:105], v[164:167], v[188:191], v[102:105]
	v_mfma_f32_16x16x32_bf16 v[98:101], v[172:175], v[188:191], v[98:101]
	v_mfma_f32_16x16x32_bf16 v[86:89], v[164:167], v[208:211], v[86:89]
	v_mfma_f32_16x16x32_bf16 v[82:85], v[172:175], v[208:211], v[82:85]
	v_mfma_f32_16x16x32_bf16 v[70:73], v[164:167], v[216:219], v[70:73]
	v_mfma_f32_16x16x32_bf16 v[66:69], v[172:175], v[216:219], v[66:69]
	s_setprio 0
	s_barrier
; #define PG8_STAGE(bufoff, gbase, voff) do { _Pragma("unroll") for (int _i = 0; _i < 2; ++_i) \
;         __builtin_amdgcn_global_load_lds((const unsigned*)((const char*)(gbase) + (voff)[_i]), (PG8_LAS unsigned*)(lds + (bufoff) + ldsw + _i * 8192), 16, 0, 0); } while (0)
; #define PG8_LDA(dst, b, h) do { _Pragma("unroll") for (int m = 0; m < 4; ++m) _Pragma("unroll") for (int k = 0; k < 2; ++k) dst[m][k] = *(const PG8_LAS bf16x8*)(lds + PG8_SA(b, h) + aoff + m * 2048 + k * 1024); } while (0)
; #define PG8_MMA(ai, bj, At, Bt) do { __builtin_amdgcn_s_setprio(1); _Pragma("unroll") for (int m = 0; m < 4; ++m) _Pragma("unroll") for (int n = 0; n < 2; ++n) _Pragma("unroll") for (int k = 0; k < 2; ++k) \
;         acc[ai][bj][m][n] = __builtin_amdgcn_mfma_f32_16x16x32_bf16(Bt[n][k], At[m][k], acc[ai][bj][m][n], 0, 0, 0); __builtin_amdgcn_s_setprio(0); } while (0)
; #define PG8_WAIT_V(n) asm volatile("s_waitcnt vmcnt(" #n ")" ::: "memory")
; #define PG8_WAIT_L(n) asm volatile("s_waitcnt lgkmcnt(" #n ")" ::: "memory")
; #define PG8_BAR __builtin_amdgcn_s_barrier()
; #define PG8_SCHED __builtin_amdgcn_sched_barrier(0)
; template <class Epi, class Sched, bool ALIGN_EPI = false, bool SP2 = false>
; __device__ __forceinline__ void gemm_phase(PG8_LAS unsigned char* lds, const Gemm g, const Sched& S, const Epi& E, int tid_in) {
;     ...
;             PG8_LDA(At, 1, 1); PG8_STAGE(PG8_SB(1, 0), b3, voffB); PG8_STAGE(PG8_SB(1, 1), b3 + hstep, voffB); PG8_STAGE(PG8_SA(1, 0), a3, voffA);
;             PG8_WAIT_V(8); PG8_WAIT_L(0); PG8_BAR; PG8_MMA(1, 0, At, B0); PG8_MMA(1, 1, At, B1); PG8_BAR; PG8_SCHED;
	s_add_i32 s22, s45, s28
	v_lshl_add_u64 v[192:193], v[192:193], 0, s[84:85]
	s_mov_b32 m0, s22
	ds_read_b128 v[176:179], v151 offset:49152
	ds_read_b128 v[180:183], v151 offset:50176
	ds_read_b128 v[184:187], v151 offset:51200
	ds_read_b128 v[188:191], v151 offset:52224
	ds_read_b128 v[204:207], v151 offset:53248
	ds_read_b128 v[208:211], v151 offset:54272
	ds_read_b128 v[212:215], v151 offset:55296
	ds_read_b128 v[216:219], v151 offset:56320
	global_load_lds_dwordx4 v[192:193], off
	s_add_i32 m0, s22, 0x2000
	s_add_u32 s20, s20, 0x40080
	v_lshl_add_u64 v[192:193], v[220:221], 0, s[84:85]
	s_addc_u32 s21, s21, 0
	s_add_i32 s22, s46, s28
	global_load_lds_dwordx4 v[192:193], off
	v_lshl_add_u64 v[192:193], s[20:21], 0, v[32:33]
	s_mov_b32 m0, s22
	s_nop 0
	global_load_lds_dwordx4 v[192:193], off
	v_lshl_add_u64 v[192:193], s[20:21], 0, v[130:131]
	s_add_i32 m0, s22, 0x2000
	s_nop 0
	global_load_lds_dwordx4 v[192:193], off
	v_lshl_add_u64 v[192:193], v[222:223], 0, s[84:85]
	s_mov_b32 m0, s35
	s_nop 0
	global_load_lds_dwordx4 v[192:193], off
	v_lshl_add_u64 v[192:193], v[224:225], 0, s[84:85]
	s_mov_b32 m0, s36
	s_nop 0
	global_load_lds_dwordx4 v[192:193], off
	s_waitcnt vmcnt(8)
	s_waitcnt lgkmcnt(0)
	s_barrier
	s_setprio 1
	s_waitcnt lgkmcnt(0)
	v_mfma_f32_16x16x32_bf16 v[62:65], v[140:143], v[176:179], v[62:65]
	v_mfma_f32_16x16x32_bf16 v[58:61], v[152:155], v[176:179], v[58:61]
	v_mfma_f32_16x16x32_bf16 v[46:49], v[140:143], v[184:187], v[46:49]
	v_mfma_f32_16x16x32_bf16 v[42:45], v[152:155], v[184:187], v[42:45]
	v_mfma_f32_16x16x32_bf16 v[28:31], v[140:143], v[204:207], v[28:31]
	v_mfma_f32_16x16x32_bf16 v[24:27], v[152:155], v[204:207], v[24:27]
	v_mfma_f32_16x16x32_bf16 v[12:15], v[140:143], v[212:215], v[12:15]
	v_mfma_f32_16x16x32_bf16 v[8:11], v[152:155], v[212:215], v[8:11]
	v_mfma_f32_16x16x32_bf16 v[62:65], v[144:147], v[180:183], v[62:65]
	v_mfma_f32_16x16x32_bf16 v[58:61], v[156:159], v[180:183], v[58:61]
	v_mfma_f32_16x16x32_bf16 v[46:49], v[144:147], v[188:191], v[46:49]
	v_mfma_f32_16x16x32_bf16 v[42:45], v[156:159], v[188:191], v[42:45]
	v_mfma_f32_16x16x32_bf16 v[28:31], v[144:147], v[208:211], v[28:31]
	v_mfma_f32_16x16x32_bf16 v[24:27], v[156:159], v[208:211], v[24:27]
	v_mfma_f32_16x16x32_bf16 v[12:15], v[144:147], v[216:219], v[12:15]
	v_mfma_f32_16x16x32_bf16 v[8:11], v[156:159], v[216:219], v[8:11]
	s_setprio 0
	s_setprio 1
	v_mfma_f32_16x16x32_bf16 v[54:57], v[160:163], v[176:179], v[54:57]
	v_mfma_f32_16x16x32_bf16 v[50:53], v[168:171], v[176:179], v[50:53]
	v_mfma_f32_16x16x32_bf16 v[38:41], v[160:163], v[184:187], v[38:41]
	v_mfma_f32_16x16x32_bf16 v[34:37], v[168:171], v[184:187], v[34:37]
	v_mfma_f32_16x16x32_bf16 v[20:23], v[160:163], v[204:207], v[20:23]
	v_mfma_f32_16x16x32_bf16 v[16:19], v[168:171], v[204:207], v[16:19]
	v_mfma_f32_16x16x32_bf16 v[4:7], v[160:163], v[212:215], v[4:7]
	v_mfma_f32_16x16x32_bf16 v[0:3], v[168:171], v[212:215], v[0:3]
	v_mfma_f32_16x16x32_bf16 v[54:57], v[164:167], v[180:183], v[54:57]
	v_mfma_f32_16x16x32_bf16 v[50:53], v[172:175], v[180:183], v[50:53]
	v_mfma_f32_16x16x32_bf16 v[38:41], v[164:167], v[188:191], v[38:41]
	v_mfma_f32_16x16x32_bf16 v[34:37], v[172:175], v[188:191], v[34:37]
	v_mfma_f32_16x16x32_bf16 v[20:23], v[164:167], v[208:211], v[20:23]
	v_mfma_f32_16x16x32_bf16 v[16:19], v[172:175], v[208:211], v[16:19]
	v_mfma_f32_16x16x32_bf16 v[4:7], v[164:167], v[216:219], v[4:7]
	v_mfma_f32_16x16x32_bf16 v[0:3], v[172:175], v[216:219], v[0:3]
	s_setprio 0
	s_barrier
	s_add_i32 s44, s44, 2
	s_add_u32 s6, s6, 0x100
	s_addc_u32 s7, s7, 0
	s_add_u32 s42, s42, 0x100
	s_addc_u32 s43, s43, 0
	s_cmp_gt_u32 s44, 13
	s_cbranch_scc0 .LBB0_388
	s_and_b64 vcc, exec, s[10:11]
	s_cbranch_vccz .LBB0_391
	s_barrier

; #define PG8_STAGE(bufoff, gbase, voff) do { _Pragma("unroll") for (int _i = 0; _i < 2; ++_i) \
;         __builtin_amdgcn_global_load_lds((const unsigned*)((const char*)(gbase) + (voff)[_i]), (PG8_LAS unsigned*)(lds + (bufoff) + ldsw + _i * 8192), 16, 0, 0); } while (0)
; #define PG8_LDA(dst, b, h) do { _Pragma("unroll") for (int m = 0; m < 4; ++m) _Pragma("unroll") for (int k = 0; k < 2; ++k) dst[m][k] = *(const PG8_LAS bf16x8*)(lds + PG8_SA(b, h) + aoff + m * 2048 + k * 1024); } while (0)
; #define PG8_LDB(dst, b, h) do { _Pragma("unroll") for (int n = 0; n < 2; ++n) _Pragma("unroll") for (int k = 0; k < 2; ++k) dst[n][k] = *(const PG8_LAS bf16x8*)(lds + PG8_SB(b, h) + boff + n * 2048 + k * 1024); } while (0)
; #define PG8_MMA(ai, bj, At, Bt) do { __builtin_amdgcn_s_setprio(1); _Pragma("unroll") for (int m = 0; m < 4; ++m) _Pragma("unroll") for (int n = 0; n < 2; ++n) _Pragma("unroll") for (int k = 0; k < 2; ++k) \
;         acc[ai][bj][m][n] = __builtin_amdgcn_mfma_f32_16x16x32_bf16(Bt[n][k], At[m][k], acc[ai][bj][m][n], 0, 0, 0); __builtin_amdgcn_s_setprio(0); } while (0)
; #define PG8_WAIT_V(n) asm volatile("s_waitcnt vmcnt(" #n ")" ::: "memory")
; #define PG8_WAIT_L(n) asm volatile("s_waitcnt lgkmcnt(" #n ")" ::: "memory")
; template <class Epi, class Sched, bool ALIGN_EPI = false, bool SP2 = false>
; __device__ __forceinline__ void gemm_phase(PG8_LAS unsigned char* lds, const Gemm g, const Sched& S, const Epi& E, int tid_in) {
;     ...
;             const bool last = (t == nt - 2);
;             const char* a1 = cA + (size_t)(t + 1) * kstep;
;             const char* a2 = last ? nA : cA + (size_t)(t + 2) * kstep; const char* b2 = last ? nB : cB + (size_t)(t + 2) * kstep;
;             const char* a3 = a2 + kstep; const char* b3 = b2 + kstep;
;             if (last && has_next) S.a_ready(nxt);
;             if constexpr (SP2) {
;             PG8_LDB(B0, 0, 0); PG8_LDB(B1, 0, 1); PG8_SCHED; PG8_LDA(At, 0, 0); PG8_STAGE(PG8_SA(1, 1), a1 + hstep, voffA);
;             PG8_WAIT_V(8); PG8_WAIT_L(0); PG8_BAR; PG8_MMA(0, 0, At, B0); PG8_MMA(0, 1, At, B1); PG8_BAR; PG8_SCHED;
;             PG8_LDA(At, 0, 1); PG8_STAGE(PG8_SB(0, 0), b2, voffB); PG8_STAGE(PG8_SB(0, 1), b2 + hstep, voffB); PG8_STAGE(PG8_SA(0, 0), a2, voffA);
;             PG8_WAIT_V(8); PG8_WAIT_L(0); PG8_BAR; PG8_MMA(1, 0, At, B0); PG8_MMA(1, 1, At, B1); PG8_BAR; PG8_SCHED;
.LBB0_920:
	s_setprio 0
	s_add_u32 s26, s2, 0xfffc0080
	s_addc_u32 s27, s3, -1
	s_add_i32 s51, 0, 0x10000
	s_cmp_eq_u32 s50, 12
	s_cselect_b32 s29, s21, s27
	s_cselect_b32 s28, s46, s26
	s_cselect_b32 s27, s19, s49
	s_cselect_b32 s26, s47, s48
	s_add_i32 s54, 0, 0x14000
	v_add_u32_e32 v142, s51, v217
	v_add_u32_e32 v158, s54, v217
	ds_read_b128 v[130:133], v142
	ds_read_b128 v[134:137], v142 offset:1024
	ds_read_b128 v[138:141], v142 offset:2048
	ds_read_b128 v[142:145], v142 offset:3072
	ds_read_b128 v[146:149], v158
	ds_read_b128 v[150:153], v158 offset:1024
	ds_read_b128 v[154:157], v158 offset:2048
	ds_read_b128 v[158:161], v158 offset:3072
	v_lshl_add_u64 v[192:193], s[2:3], 0, v[184:185]
	s_add_i32 m0, s37, 0xc000
	ds_read_b128 v[162:165], v219
	ds_read_b128 v[166:169], v219 offset:1024
	ds_read_b128 v[170:173], v219 offset:2048
	ds_read_b128 v[174:177], v219 offset:3072
	ds_read_b128 v[188:191], v219 offset:4096
	ds_read_b128 v[204:207], v219 offset:5120
	ds_read_b128 v[208:211], v219 offset:6144
	ds_read_b128 v[212:215], v219 offset:7168
	global_load_lds_dwordx4 v[192:193], off
	v_lshl_add_u64 v[192:193], s[2:3], 0, v[186:187]
	s_add_i32 m0, s37, 0xe000
	s_nop 0
	global_load_lds_dwordx4 v[192:193], off
	s_waitcnt vmcnt(8)
	s_waitcnt lgkmcnt(0)
	s_barrier
	s_setprio 1
	s_waitcnt lgkmcnt(0)
	v_mfma_f32_16x16x32_bf16 v[126:129], v[130:133], v[162:165], v[126:129]
	v_mfma_f32_16x16x32_bf16 v[122:125], v[138:141], v[162:165], v[122:125]
	v_mfma_f32_16x16x32_bf16 v[110:113], v[130:133], v[170:173], v[110:113]
	v_mfma_f32_16x16x32_bf16 v[106:109], v[138:141], v[170:173], v[106:109]
	v_mfma_f32_16x16x32_bf16 v[94:97], v[130:133], v[188:191], v[94:97]
	v_mfma_f32_16x16x32_bf16 v[90:93], v[138:141], v[188:191], v[90:93]
	v_mfma_f32_16x16x32_bf16 v[78:81], v[130:133], v[208:211], v[78:81]
	v_mfma_f32_16x16x32_bf16 v[74:77], v[138:141], v[208:211], v[74:77]
	v_mfma_f32_16x16x32_bf16 v[126:129], v[134:137], v[166:169], v[126:129]
	v_mfma_f32_16x16x32_bf16 v[122:125], v[142:145], v[166:169], v[122:125]
	v_mfma_f32_16x16x32_bf16 v[110:113], v[134:137], v[174:177], v[110:113]
	v_mfma_f32_16x16x32_bf16 v[106:109], v[142:145], v[174:177], v[106:109]
	v_mfma_f32_16x16x32_bf16 v[94:97], v[134:137], v[204:207], v[94:97]
	v_mfma_f32_16x16x32_bf16 v[90:93], v[142:145], v[204:207], v[90:93]
	v_mfma_f32_16x16x32_bf16 v[78:81], v[134:137], v[212:215], v[78:81]
	v_mfma_f32_16x16x32_bf16 v[74:77], v[142:145], v[212:215], v[74:77]
	s_setprio 0
	s_setprio 1
	v_mfma_f32_16x16x32_bf16 v[118:121], v[146:149], v[162:165], v[118:121]
	v_mfma_f32_16x16x32_bf16 v[114:117], v[154:157], v[162:165], v[114:117]
	v_mfma_f32_16x16x32_bf16 v[102:105], v[146:149], v[170:173], v[102:105]
	v_mfma_f32_16x16x32_bf16 v[98:101], v[154:157], v[170:173], v[98:101]
	v_mfma_f32_16x16x32_bf16 v[86:89], v[146:149], v[188:191], v[86:89]
	v_mfma_f32_16x16x32_bf16 v[82:85], v[154:157], v[188:191], v[82:85]
	v_mfma_f32_16x16x32_bf16 v[70:73], v[146:149], v[208:211], v[70:73]
	v_mfma_f32_16x16x32_bf16 v[66:69], v[154:157], v[208:211], v[66:69]
	v_mfma_f32_16x16x32_bf16 v[118:121], v[150:153], v[166:169], v[118:121]
	v_mfma_f32_16x16x32_bf16 v[114:117], v[158:161], v[166:169], v[114:117]
	v_mfma_f32_16x16x32_bf16 v[102:105], v[150:153], v[174:177], v[102:105]
	v_mfma_f32_16x16x32_bf16 v[98:101], v[158:161], v[174:177], v[98:101]
	v_mfma_f32_16x16x32_bf16 v[86:89], v[150:153], v[204:207], v[86:89]
	v_mfma_f32_16x16x32_bf16 v[82:85], v[158:161], v[204:207], v[82:85]
	v_mfma_f32_16x16x32_bf16 v[70:73], v[150:153], v[212:215], v[70:73]
	v_mfma_f32_16x16x32_bf16 v[66:69], v[158:161], v[212:215], v[66:69]
	s_setprio 0
	s_barrier
	s_add_i32 s51, s51, s36
	v_lshl_add_u64 v[192:193], s[26:27], 0, v[32:33]
	s_mov_b32 m0, s51
	ds_read_b128 v[162:165], v219 offset:16384
	ds_read_b128 v[166:169], v219 offset:17408
	ds_read_b128 v[170:173], v219 offset:18432
	ds_read_b128 v[174:177], v219 offset:19456
	ds_read_b128 v[188:191], v219 offset:20480
	ds_read_b128 v[204:207], v219 offset:21504
	ds_read_b128 v[208:211], v219 offset:22528
	ds_read_b128 v[212:215], v219 offset:23552
	global_load_lds_dwordx4 v[192:193], off
	s_add_i32 m0, s51, 0x2000
	s_add_u32 s52, s26, 0x40000
	v_lshl_add_u64 v[220:221], s[26:27], 0, v[178:179]
	s_addc_u32 s53, s27, 0
	s_add_i32 s51, s54, s36
	global_load_lds_dwordx4 v[220:221], off
	v_lshl_add_u64 v[222:223], s[52:53], 0, v[32:33]
	s_mov_b32 m0, s51
	v_lshl_add_u64 v[224:225], s[28:29], 0, v[180:181]
	global_load_lds_dwordx4 v[222:223], off
	v_lshl_add_u64 v[222:223], s[52:53], 0, v[178:179]
	s_add_i32 m0, s51, 0x2000
	s_nop 0
	global_load_lds_dwordx4 v[222:223], off
	v_lshl_add_u64 v[222:223], s[28:29], 0, v[182:183]
	s_mov_b32 m0, s37
	s_nop 0
	global_load_lds_dwordx4 v[222:223], off
	s_mov_b32 m0, s38
	s_nop 0
	global_load_lds_dwordx4 v[224:225], off
	s_waitcnt vmcnt(8)
	s_waitcnt lgkmcnt(0)
	s_barrier
; #define PG8_STAGE(bufoff, gbase, voff) do { _Pragma("unroll") for (int _i = 0; _i < 2; ++_i) \
;         __builtin_amdgcn_global_load_lds((const unsigned*)((const char*)(gbase) + (voff)[_i]), (PG8_LAS unsigned*)(lds + (bufoff) + ldsw + _i * 8192), 16, 0, 0); } while (0)
; #define PG8_LDA(dst, b, h) do { _Pragma("unroll") for (int m = 0; m < 4; ++m) _Pragma("unroll") for (int k = 0; k < 2; ++k) dst[m][k] = *(const PG8_LAS bf16x8*)(lds + PG8_SA(b, h) + aoff + m * 2048 + k * 1024); } while (0)
; #define PG8_LDB(dst, b, h) do { _Pragma("unroll") for (int n = 0; n < 2; ++n) _Pragma("unroll") for (int k = 0; k < 2; ++k) dst[n][k] = *(const PG8_LAS bf16x8*)(lds + PG8_SB(b, h) + boff + n * 2048 + k * 1024); } while (0)
; #define PG8_MMA(ai, bj, At, Bt) do { __builtin_amdgcn_s_setprio(1); _Pragma("unroll") for (int m = 0; m < 4; ++m) _Pragma("unroll") for (int n = 0; n < 2; ++n) _Pragma("unroll") for (int k = 0; k < 2; ++k) \
;         acc[ai][bj][m][n] = __builtin_amdgcn_mfma_f32_16x16x32_bf16(Bt[n][k], At[m][k], acc[ai][bj][m][n], 0, 0, 0); __builtin_amdgcn_s_setprio(0); } while (0)
; #define PG8_WAIT_V(n) asm volatile("s_waitcnt vmcnt(" #n ")" ::: "memory")
; #define PG8_WAIT_L(n) asm volatile("s_waitcnt lgkmcnt(" #n ")" ::: "memory")
; #define PG8_BAR __builtin_amdgcn_s_barrier()
; #define PG8_SCHED __builtin_amdgcn_sched_barrier(0)
; template <class Epi, class Sched, bool ALIGN_EPI = false, bool SP2 = false>
; __device__ __forceinline__ void gemm_phase(PG8_LAS unsigned char* lds, const Gemm g, const Sched& S, const Epi& E, int tid_in) {
;     ...
;             PG8_WAIT_V(8); PG8_WAIT_L(0); PG8_BAR; PG8_MMA(1, 0, At, B0); PG8_MMA(1, 1, At, B1); PG8_BAR; PG8_SCHED;
;             PG8_LDB(B0, 1, 0); PG8_LDB(B1, 1, 1); PG8_SCHED; PG8_LDA(At, 1, 0); PG8_STAGE(PG8_SA(0, 1), a2 + hstep, voffA);
;             PG8_WAIT_V(8); PG8_WAIT_L(0); PG8_BAR; PG8_MMA(0, 0, At, B0); PG8_MMA(0, 1, At, B1); PG8_BAR; PG8_SCHED;
	s_setprio 1
	s_waitcnt lgkmcnt(0)
	v_mfma_f32_16x16x32_bf16 v[62:65], v[130:133], v[162:165], v[62:65]
	v_mfma_f32_16x16x32_bf16 v[58:61], v[138:141], v[162:165], v[58:61]
	v_mfma_f32_16x16x32_bf16 v[46:49], v[130:133], v[170:173], v[46:49]
	v_mfma_f32_16x16x32_bf16 v[42:45], v[138:141], v[170:173], v[42:45]
	v_mfma_f32_16x16x32_bf16 v[28:31], v[130:133], v[188:191], v[28:31]
	v_mfma_f32_16x16x32_bf16 v[24:27], v[138:141], v[188:191], v[24:27]
	v_mfma_f32_16x16x32_bf16 v[12:15], v[130:133], v[208:211], v[12:15]
	v_mfma_f32_16x16x32_bf16 v[8:11], v[138:141], v[208:211], v[8:11]
	v_mfma_f32_16x16x32_bf16 v[62:65], v[134:137], v[166:169], v[62:65]
	v_mfma_f32_16x16x32_bf16 v[58:61], v[142:145], v[166:169], v[58:61]
	v_mfma_f32_16x16x32_bf16 v[46:49], v[134:137], v[174:177], v[46:49]
	v_mfma_f32_16x16x32_bf16 v[42:45], v[142:145], v[174:177], v[42:45]
	v_mfma_f32_16x16x32_bf16 v[28:31], v[134:137], v[204:207], v[28:31]
	v_mfma_f32_16x16x32_bf16 v[24:27], v[142:145], v[204:207], v[24:27]
	v_mfma_f32_16x16x32_bf16 v[12:15], v[134:137], v[212:215], v[12:15]
	v_mfma_f32_16x16x32_bf16 v[8:11], v[142:145], v[212:215], v[8:11]
	s_setprio 0
	s_setprio 1
	v_mfma_f32_16x16x32_bf16 v[54:57], v[146:149], v[162:165], v[54:57]
	v_mfma_f32_16x16x32_bf16 v[50:53], v[154:157], v[162:165], v[50:53]
	v_mfma_f32_16x16x32_bf16 v[38:41], v[146:149], v[170:173], v[38:41]
	v_mfma_f32_16x16x32_bf16 v[34:37], v[154:157], v[170:173], v[34:37]
	v_mfma_f32_16x16x32_bf16 v[20:23], v[146:149], v[188:191], v[20:23]
	v_mfma_f32_16x16x32_bf16 v[16:19], v[154:157], v[188:191], v[16:19]
	v_mfma_f32_16x16x32_bf16 v[4:7], v[146:149], v[208:211], v[4:7]
	v_mfma_f32_16x16x32_bf16 v[0:3], v[154:157], v[208:211], v[0:3]
	v_mfma_f32_16x16x32_bf16 v[54:57], v[150:153], v[166:169], v[54:57]
	v_mfma_f32_16x16x32_bf16 v[50:53], v[158:161], v[166:169], v[50:53]
	v_mfma_f32_16x16x32_bf16 v[38:41], v[150:153], v[174:177], v[38:41]
	v_mfma_f32_16x16x32_bf16 v[34:37], v[158:161], v[174:177], v[34:37]
	v_mfma_f32_16x16x32_bf16 v[20:23], v[150:153], v[204:207], v[20:23]
	v_mfma_f32_16x16x32_bf16 v[16:19], v[158:161], v[204:207], v[16:19]
	v_mfma_f32_16x16x32_bf16 v[4:7], v[150:153], v[212:215], v[4:7]
	v_mfma_f32_16x16x32_bf16 v[0:3], v[158:161], v[212:215], v[0:3]
	s_setprio 0
	s_barrier
	s_add_i32 s51, 0, 0x18000
	s_add_i32 s52, 0, 0x1c000
	v_add_u32_e32 v142, s51, v217
	v_add_u32_e32 v158, s52, v217
	ds_read_b128 v[130:133], v142
	ds_read_b128 v[134:137], v142 offset:1024
	ds_read_b128 v[138:141], v142 offset:2048
	ds_read_b128 v[142:145], v142 offset:3072
	ds_read_b128 v[146:149], v158
	ds_read_b128 v[150:153], v158 offset:1024
	ds_read_b128 v[154:157], v158 offset:2048
	ds_read_b128 v[158:161], v158 offset:3072
	s_add_u32 s28, s28, 0x40000
	s_addc_u32 s29, s29, 0
	s_mov_b32 m0, s39
	v_lshl_add_u64 v[226:227], s[28:29], 0, v[182:183]
	ds_read_b128 v[162:165], v219 offset:32768
	ds_read_b128 v[166:169], v219 offset:33792
	ds_read_b128 v[170:173], v219 offset:34816
	ds_read_b128 v[174:177], v219 offset:35840
	ds_read_b128 v[188:191], v219 offset:36864
	ds_read_b128 v[204:207], v219 offset:37888
	ds_read_b128 v[208:211], v219 offset:38912
	ds_read_b128 v[212:215], v219 offset:39936
	global_load_lds_dwordx4 v[226:227], off
	v_lshl_add_u64 v[226:227], s[28:29], 0, v[180:181]
	s_mov_b32 m0, s40
	s_nop 0
	global_load_lds_dwordx4 v[226:227], off
	s_waitcnt vmcnt(8)
	s_waitcnt lgkmcnt(0)
	s_barrier
	s_setprio 1
	s_waitcnt lgkmcnt(0)
	v_mfma_f32_16x16x32_bf16 v[126:129], v[130:133], v[162:165], v[126:129]
	v_mfma_f32_16x16x32_bf16 v[122:125], v[138:141], v[162:165], v[122:125]
	v_mfma_f32_16x16x32_bf16 v[110:113], v[130:133], v[170:173], v[110:113]
	v_mfma_f32_16x16x32_bf16 v[106:109], v[138:141], v[170:173], v[106:109]
	v_mfma_f32_16x16x32_bf16 v[94:97], v[130:133], v[188:191], v[94:97]
	v_mfma_f32_16x16x32_bf16 v[90:93], v[138:141], v[188:191], v[90:93]
	v_mfma_f32_16x16x32_bf16 v[78:81], v[130:133], v[208:211], v[78:81]
	v_mfma_f32_16x16x32_bf16 v[74:77], v[138:141], v[208:211], v[74:77]
	v_mfma_f32_16x16x32_bf16 v[126:129], v[134:137], v[166:169], v[126:129]
	v_mfma_f32_16x16x32_bf16 v[122:125], v[142:145], v[166:169], v[122:125]
	v_mfma_f32_16x16x32_bf16 v[110:113], v[134:137], v[174:177], v[110:113]
	v_mfma_f32_16x16x32_bf16 v[106:109], v[142:145], v[174:177], v[106:109]
	v_mfma_f32_16x16x32_bf16 v[94:97], v[134:137], v[204:207], v[94:97]
	v_mfma_f32_16x16x32_bf16 v[90:93], v[142:145], v[204:207], v[90:93]
	v_mfma_f32_16x16x32_bf16 v[78:81], v[134:137], v[212:215], v[78:81]
	v_mfma_f32_16x16x32_bf16 v[74:77], v[142:145], v[212:215], v[74:77]
	s_setprio 0
	s_setprio 1
	v_mfma_f32_16x16x32_bf16 v[118:121], v[146:149], v[162:165], v[118:121]
	v_mfma_f32_16x16x32_bf16 v[114:117], v[154:157], v[162:165], v[114:117]
	v_mfma_f32_16x16x32_bf16 v[102:105], v[146:149], v[170:173], v[102:105]
	v_mfma_f32_16x16x32_bf16 v[98:101], v[154:157], v[170:173], v[98:101]
	v_mfma_f32_16x16x32_bf16 v[86:89], v[146:149], v[188:191], v[86:89]
	v_mfma_f32_16x16x32_bf16 v[82:85], v[154:157], v[188:191], v[82:85]
	v_mfma_f32_16x16x32_bf16 v[70:73], v[146:149], v[208:211], v[70:73]
	v_mfma_f32_16x16x32_bf16 v[66:69], v[154:157], v[208:211], v[66:69]
	v_mfma_f32_16x16x32_bf16 v[118:121], v[150:153], v[166:169], v[118:121]
	v_mfma_f32_16x16x32_bf16 v[114:117], v[158:161], v[166:169], v[114:117]
	v_mfma_f32_16x16x32_bf16 v[102:105], v[150:153], v[174:177], v[102:105]
	v_mfma_f32_16x16x32_bf16 v[98:101], v[158:161], v[174:177], v[98:101]
	v_mfma_f32_16x16x32_bf16 v[86:89], v[150:153], v[204:207], v[86:89]
	v_mfma_f32_16x16x32_bf16 v[82:85], v[158:161], v[204:207], v[82:85]
	v_mfma_f32_16x16x32_bf16 v[70:73], v[150:153], v[212:215], v[70:73]
	v_mfma_f32_16x16x32_bf16 v[66:69], v[158:161], v[212:215], v[66:69]
	s_setprio 0
	s_barrier
; #define PG8_STAGE(bufoff, gbase, voff) do { _Pragma("unroll") for (int _i = 0; _i < 2; ++_i) \
;         __builtin_amdgcn_global_load_lds((const unsigned*)((const char*)(gbase) + (voff)[_i]), (PG8_LAS unsigned*)(lds + (bufoff) + ldsw + _i * 8192), 16, 0, 0); } while (0)
; #define PG8_LDA(dst, b, h) do { _Pragma("unroll") for (int m = 0; m < 4; ++m) _Pragma("unroll") for (int k = 0; k < 2; ++k) dst[m][k] = *(const PG8_LAS bf16x8*)(lds + PG8_SA(b, h) + aoff + m * 2048 + k * 1024); } while (0)
; #define PG8_MMA(ai, bj, At, Bt) do { __builtin_amdgcn_s_setprio(1); _Pragma("unroll") for (int m = 0; m < 4; ++m) _Pragma("unroll") for (int n = 0; n < 2; ++n) _Pragma("unroll") for (int k = 0; k < 2; ++k) \
;         acc[ai][bj][m][n] = __builtin_amdgcn_mfma_f32_16x16x32_bf16(Bt[n][k], At[m][k], acc[ai][bj][m][n], 0, 0, 0); __builtin_amdgcn_s_setprio(0); } while (0)
; #define PG8_WAIT_V(n) asm volatile("s_waitcnt vmcnt(" #n ")" ::: "memory")
; #define PG8_WAIT_L(n) asm volatile("s_waitcnt lgkmcnt(" #n ")" ::: "memory")
; #define PG8_BAR __builtin_amdgcn_s_barrier()
; #define PG8_SCHED __builtin_amdgcn_sched_barrier(0)
; template <class Epi, class Sched, bool ALIGN_EPI = false, bool SP2 = false>
; __device__ __forceinline__ void gemm_phase(PG8_LAS unsigned char* lds, const Gemm g, const Sched& S, const Epi& E, int tid_in) {
;     ...
;             PG8_LDA(At, 1, 1); PG8_STAGE(PG8_SB(1, 0), b3, voffB); PG8_STAGE(PG8_SB(1, 1), b3 + hstep, voffB); PG8_STAGE(PG8_SA(1, 0), a3, voffA);
;             PG8_WAIT_V(8); PG8_WAIT_L(0); PG8_BAR; PG8_MMA(1, 0, At, B0); PG8_MMA(1, 1, At, B1); PG8_BAR; PG8_SCHED;
;     ...
;         if constexpr (ALIGN_EPI) { if (wr == 0) PG8_BAR; }
	s_add_i32 s28, s51, s36
	v_lshl_add_u64 v[192:193], v[192:193], 0, s[84:85]
	s_mov_b32 m0, s28
	ds_read_b128 v[162:165], v219 offset:49152
	ds_read_b128 v[166:169], v219 offset:50176
	ds_read_b128 v[170:173], v219 offset:51200
	ds_read_b128 v[174:177], v219 offset:52224
	ds_read_b128 v[188:191], v219 offset:53248
	ds_read_b128 v[204:207], v219 offset:54272
	ds_read_b128 v[208:211], v219 offset:55296
	ds_read_b128 v[212:215], v219 offset:56320
	global_load_lds_dwordx4 v[192:193], off
	s_add_i32 m0, s28, 0x2000
	s_add_u32 s26, s26, 0x40080
	v_lshl_add_u64 v[192:193], v[220:221], 0, s[84:85]
	s_addc_u32 s27, s27, 0
	s_add_i32 s28, s52, s36
	global_load_lds_dwordx4 v[192:193], off
	v_lshl_add_u64 v[192:193], s[26:27], 0, v[32:33]
	s_mov_b32 m0, s28
	s_nop 0
	global_load_lds_dwordx4 v[192:193], off
	v_lshl_add_u64 v[192:193], s[26:27], 0, v[178:179]
	s_add_i32 m0, s28, 0x2000
	s_nop 0
	global_load_lds_dwordx4 v[192:193], off
	v_lshl_add_u64 v[192:193], v[222:223], 0, s[84:85]
	s_mov_b32 m0, s41
	s_nop 0
	global_load_lds_dwordx4 v[192:193], off
	v_lshl_add_u64 v[192:193], v[224:225], 0, s[84:85]
	s_mov_b32 m0, s42
	s_nop 0
	global_load_lds_dwordx4 v[192:193], off
	s_waitcnt vmcnt(8)
	s_waitcnt lgkmcnt(0)
	s_barrier
	s_setprio 1
	s_waitcnt lgkmcnt(0)
	v_mfma_f32_16x16x32_bf16 v[62:65], v[130:133], v[162:165], v[62:65]
	v_mfma_f32_16x16x32_bf16 v[58:61], v[138:141], v[162:165], v[58:61]
	v_mfma_f32_16x16x32_bf16 v[46:49], v[130:133], v[170:173], v[46:49]
	v_mfma_f32_16x16x32_bf16 v[42:45], v[138:141], v[170:173], v[42:45]
	v_mfma_f32_16x16x32_bf16 v[28:31], v[130:133], v[188:191], v[28:31]
	v_mfma_f32_16x16x32_bf16 v[24:27], v[138:141], v[188:191], v[24:27]
	v_mfma_f32_16x16x32_bf16 v[12:15], v[130:133], v[208:211], v[12:15]
	v_mfma_f32_16x16x32_bf16 v[8:11], v[138:141], v[208:211], v[8:11]
	v_mfma_f32_16x16x32_bf16 v[62:65], v[134:137], v[166:169], v[62:65]
	v_mfma_f32_16x16x32_bf16 v[58:61], v[142:145], v[166:169], v[58:61]
	v_mfma_f32_16x16x32_bf16 v[46:49], v[134:137], v[174:177], v[46:49]
	v_mfma_f32_16x16x32_bf16 v[42:45], v[142:145], v[174:177], v[42:45]
	v_mfma_f32_16x16x32_bf16 v[28:31], v[134:137], v[204:207], v[28:31]
	v_mfma_f32_16x16x32_bf16 v[24:27], v[142:145], v[204:207], v[24:27]
	v_mfma_f32_16x16x32_bf16 v[12:15], v[134:137], v[212:215], v[12:15]
	v_mfma_f32_16x16x32_bf16 v[8:11], v[142:145], v[212:215], v[8:11]
	s_setprio 0
	s_setprio 1
	v_mfma_f32_16x16x32_bf16 v[54:57], v[146:149], v[162:165], v[54:57]
	v_mfma_f32_16x16x32_bf16 v[50:53], v[154:157], v[162:165], v[50:53]
	v_mfma_f32_16x16x32_bf16 v[38:41], v[146:149], v[170:173], v[38:41]
	v_mfma_f32_16x16x32_bf16 v[34:37], v[154:157], v[170:173], v[34:37]
	v_mfma_f32_16x16x32_bf16 v[20:23], v[146:149], v[188:191], v[20:23]
	v_mfma_f32_16x16x32_bf16 v[16:19], v[154:157], v[188:191], v[16:19]
	v_mfma_f32_16x16x32_bf16 v[4:7], v[146:149], v[208:211], v[4:7]
	v_mfma_f32_16x16x32_bf16 v[0:3], v[154:157], v[208:211], v[0:3]
	v_mfma_f32_16x16x32_bf16 v[54:57], v[150:153], v[166:169], v[54:57]
	v_mfma_f32_16x16x32_bf16 v[50:53], v[158:161], v[166:169], v[50:53]
	v_mfma_f32_16x16x32_bf16 v[38:41], v[150:153], v[174:177], v[38:41]
	v_mfma_f32_16x16x32_bf16 v[34:37], v[158:161], v[174:177], v[34:37]
	v_mfma_f32_16x16x32_bf16 v[20:23], v[150:153], v[204:207], v[20:23]
	v_mfma_f32_16x16x32_bf16 v[16:19], v[158:161], v[204:207], v[16:19]
	v_mfma_f32_16x16x32_bf16 v[4:7], v[150:153], v[212:215], v[4:7]
	v_mfma_f32_16x16x32_bf16 v[0:3], v[158:161], v[212:215], v[0:3]
	s_setprio 0
	s_barrier
	s_add_i32 s50, s50, 2
	s_add_u32 s2, s2, 0x100
	s_addc_u32 s3, s3, 0
	s_add_u32 s48, s48, 0x100
	s_addc_u32 s49, s49, 0
	s_cmp_gt_u32 s50, 13
	s_cbranch_scc0 .LBB0_920
	s_and_b64 vcc, exec, s[16:17]
	s_cbranch_vccz .LBB0_923
	s_barrier
.LBB0_923:
	s_cmp_eq_u64 s[16:17], 0
	s_cbranch_scc0 .Lge_np3
	s_setprio 1

; #define PG8_STAGE(bufoff, gbase, voff) do { _Pragma("unroll") for (int _i = 0; _i < 2; ++_i) \
;         __builtin_amdgcn_global_load_lds((const unsigned*)((const char*)(gbase) + (voff)[_i]), (PG8_LAS unsigned*)(lds + (bufoff) + ldsw + _i * 8192), 16, 0, 0); } while (0)
; #define PG8_LDA(dst, b, h) do { _Pragma("unroll") for (int m = 0; m < 4; ++m) _Pragma("unroll") for (int k = 0; k < 2; ++k) dst[m][k] = *(const PG8_LAS bf16x8*)(lds + PG8_SA(b, h) + aoff + m * 2048 + k * 1024); } while (0)
; #define PG8_LDB(dst, b, h) do { _Pragma("unroll") for (int n = 0; n < 2; ++n) _Pragma("unroll") for (int k = 0; k < 2; ++k) dst[n][k] = *(const PG8_LAS bf16x8*)(lds + PG8_SB(b, h) + boff + n * 2048 + k * 1024); } while (0)
; #define PG8_MMA(ai, bj, At, Bt) do { __builtin_amdgcn_s_setprio(1); _Pragma("unroll") for (int m = 0; m < 4; ++m) _Pragma("unroll") for (int n = 0; n < 2; ++n) _Pragma("unroll") for (int k = 0; k < 2; ++k) \
;         acc[ai][bj][m][n] = __builtin_amdgcn_mfma_f32_16x16x32_bf16(Bt[n][k], At[m][k], acc[ai][bj][m][n], 0, 0, 0); __builtin_amdgcn_s_setprio(0); } while (0)
; #define PG8_WAIT_V(n) asm volatile("s_waitcnt vmcnt(" #n ")" ::: "memory")
; #define PG8_WAIT_L(n) asm volatile("s_waitcnt lgkmcnt(" #n ")" ::: "memory")
; template <class Epi, class Sched, bool ALIGN_EPI = false, bool SP2 = false>
; __device__ __forceinline__ void gemm_phase(PG8_LAS unsigned char* lds, const Gemm g, const Sched& S, const Epi& E, int tid_in) {
;     ...
;             const bool last = (t == nt - 2);
;             const char* a1 = cA + (size_t)(t + 1) * kstep;
;             const char* a2 = last ? nA : cA + (size_t)(t + 2) * kstep; const char* b2 = last ? nB : cB + (size_t)(t + 2) * kstep;
;             const char* a3 = a2 + kstep; const char* b3 = b2 + kstep;
;             if (last && has_next) S.a_ready(nxt);
;             if constexpr (SP2) {
;             PG8_LDB(B0, 0, 0); PG8_LDB(B1, 0, 1); PG8_SCHED; PG8_LDA(At, 0, 0); PG8_STAGE(PG8_SA(1, 1), a1 + hstep, voffA);
;             PG8_WAIT_V(8); PG8_WAIT_L(0); PG8_BAR; PG8_MMA(0, 0, At, B0); PG8_MMA(0, 1, At, B1); PG8_BAR; PG8_SCHED;
;             PG8_LDA(At, 0, 1); PG8_STAGE(PG8_SB(0, 0), b2, voffB); PG8_STAGE(PG8_SB(0, 1), b2 + hstep, voffB); PG8_STAGE(PG8_SA(0, 0), a2, voffA);
;             PG8_WAIT_V(8); PG8_WAIT_L(0); PG8_BAR; PG8_MMA(1, 0, At, B0); PG8_MMA(1, 1, At, B1); PG8_BAR; PG8_SCHED;
.LBB0_1010:
	s_setprio 0
	s_add_u32 s6, s2, 0x100
	s_addc_u32 s7, s3, 0
	s_add_i32 s52, 0, 0x10000
	s_cmp_eq_u32 s51, 40
	s_cselect_b32 s29, s23, s7
	s_cselect_b32 s28, s22, s6
	s_cselect_b32 s27, s25, s50
	s_cselect_b32 s26, s24, s49
	s_add_i32 s53, 0, 0x14000
	v_add_u32_e32 v142, s52, v248
	v_add_u32_e32 v158, s53, v248
	ds_read_b128 v[130:133], v142
	ds_read_b128 v[134:137], v142 offset:1024
	ds_read_b128 v[138:141], v142 offset:2048
	ds_read_b128 v[142:145], v142 offset:3072
	ds_read_b128 v[146:149], v158
	ds_read_b128 v[150:153], v158 offset:1024
	ds_read_b128 v[154:157], v158 offset:2048
	ds_read_b128 v[158:161], v158 offset:3072
	v_lshl_add_u64 v[214:215], s[2:3], 0, v[210:211]
	s_add_i32 m0, s38, 0xc000
	ds_read_b128 v[162:165], v250
	ds_read_b128 v[166:169], v250 offset:1024
	ds_read_b128 v[170:173], v250 offset:2048
	ds_read_b128 v[174:177], v250 offset:3072
	ds_read_b128 v[178:181], v250 offset:4096
	ds_read_b128 v[182:185], v250 offset:5120
	ds_read_b128 v[186:189], v250 offset:6144
	ds_read_b128 v[190:193], v250 offset:7168
	global_load_lds_dwordx4 v[214:215], off
	v_lshl_add_u64 v[214:215], s[2:3], 0, v[212:213]
	s_add_i32 m0, s38, 0xe000
	s_nop 0
	global_load_lds_dwordx4 v[214:215], off
	s_waitcnt vmcnt(8)
	s_waitcnt lgkmcnt(0)
	s_barrier
	s_setprio 1
	s_waitcnt lgkmcnt(0)
	v_mfma_f32_16x16x32_bf16 v[126:129], v[130:133], v[162:165], v[126:129]
	v_mfma_f32_16x16x32_bf16 v[122:125], v[138:141], v[162:165], v[122:125]
	v_mfma_f32_16x16x32_bf16 v[114:117], v[130:133], v[170:173], v[114:117]
	v_mfma_f32_16x16x32_bf16 v[106:109], v[138:141], v[170:173], v[106:109]
	v_mfma_f32_16x16x32_bf16 v[98:101], v[130:133], v[178:181], v[98:101]
	v_mfma_f32_16x16x32_bf16 v[90:93], v[138:141], v[178:181], v[90:93]
	v_mfma_f32_16x16x32_bf16 v[82:85], v[130:133], v[186:189], v[82:85]
	v_mfma_f32_16x16x32_bf16 v[74:77], v[138:141], v[186:189], v[74:77]
	v_mfma_f32_16x16x32_bf16 v[126:129], v[134:137], v[166:169], v[126:129]
	v_mfma_f32_16x16x32_bf16 v[122:125], v[142:145], v[166:169], v[122:125]
	v_mfma_f32_16x16x32_bf16 v[114:117], v[134:137], v[174:177], v[114:117]
	v_mfma_f32_16x16x32_bf16 v[106:109], v[142:145], v[174:177], v[106:109]
	v_mfma_f32_16x16x32_bf16 v[98:101], v[134:137], v[182:185], v[98:101]
	v_mfma_f32_16x16x32_bf16 v[90:93], v[142:145], v[182:185], v[90:93]
	v_mfma_f32_16x16x32_bf16 v[82:85], v[134:137], v[190:193], v[82:85]
	v_mfma_f32_16x16x32_bf16 v[74:77], v[142:145], v[190:193], v[74:77]
	s_setprio 0
	s_setprio 1
	v_mfma_f32_16x16x32_bf16 v[118:121], v[146:149], v[162:165], v[118:121]
	v_mfma_f32_16x16x32_bf16 v[110:113], v[154:157], v[162:165], v[110:113]
	v_mfma_f32_16x16x32_bf16 v[102:105], v[146:149], v[170:173], v[102:105]
	v_mfma_f32_16x16x32_bf16 v[94:97], v[154:157], v[170:173], v[94:97]
	v_mfma_f32_16x16x32_bf16 v[86:89], v[146:149], v[178:181], v[86:89]
	v_mfma_f32_16x16x32_bf16 v[78:81], v[154:157], v[178:181], v[78:81]
	v_mfma_f32_16x16x32_bf16 v[70:73], v[146:149], v[186:189], v[70:73]
	v_mfma_f32_16x16x32_bf16 v[66:69], v[154:157], v[186:189], v[66:69]
	v_mfma_f32_16x16x32_bf16 v[118:121], v[150:153], v[166:169], v[118:121]
	v_mfma_f32_16x16x32_bf16 v[110:113], v[158:161], v[166:169], v[110:113]
	v_mfma_f32_16x16x32_bf16 v[102:105], v[150:153], v[174:177], v[102:105]
	v_mfma_f32_16x16x32_bf16 v[94:97], v[158:161], v[174:177], v[94:97]
	v_mfma_f32_16x16x32_bf16 v[86:89], v[150:153], v[182:185], v[86:89]
	v_mfma_f32_16x16x32_bf16 v[78:81], v[158:161], v[182:185], v[78:81]
	v_mfma_f32_16x16x32_bf16 v[70:73], v[150:153], v[190:193], v[70:73]
	v_mfma_f32_16x16x32_bf16 v[66:69], v[158:161], v[190:193], v[66:69]
	s_setprio 0
	s_barrier
	s_add_i32 s2, s52, s31
	v_lshl_add_u64 v[214:215], s[26:27], 0, v[32:33]
	s_mov_b32 m0, s2
	ds_read_b128 v[162:165], v250 offset:16384
	ds_read_b128 v[166:169], v250 offset:17408
	ds_read_b128 v[170:173], v250 offset:18432
	ds_read_b128 v[174:177], v250 offset:19456
	ds_read_b128 v[178:181], v250 offset:20480
	ds_read_b128 v[182:185], v250 offset:21504
	ds_read_b128 v[186:189], v250 offset:22528
	ds_read_b128 v[190:193], v250 offset:23552
	global_load_lds_dwordx4 v[214:215], off
	s_add_i32 m0, s2, 0x2000
	s_add_u32 s2, s26, 0xb0000
	v_lshl_add_u64 v[216:217], s[26:27], 0, v[204:205]
	s_addc_u32 s3, s27, 0
	s_add_i32 s52, s53, s31
	global_load_lds_dwordx4 v[216:217], off
	v_lshl_add_u64 v[218:219], s[2:3], 0, v[32:33]
	s_mov_b32 m0, s52
	v_lshl_add_u64 v[220:221], s[28:29], 0, v[206:207]
	global_load_lds_dwordx4 v[218:219], off
	v_lshl_add_u64 v[218:219], s[2:3], 0, v[204:205]
	s_add_i32 m0, s52, 0x2000
	s_nop 0
	global_load_lds_dwordx4 v[218:219], off
	v_lshl_add_u64 v[218:219], s[28:29], 0, v[208:209]
	s_mov_b32 m0, s38
	s_nop 0
	global_load_lds_dwordx4 v[218:219], off
	s_mov_b32 m0, s39
	s_nop 0
	global_load_lds_dwordx4 v[220:221], off
	s_waitcnt vmcnt(8)
	s_waitcnt lgkmcnt(0)
	s_barrier
; #define PG8_STAGE(bufoff, gbase, voff) do { _Pragma("unroll") for (int _i = 0; _i < 2; ++_i) \
;         __builtin_amdgcn_global_load_lds((const unsigned*)((const char*)(gbase) + (voff)[_i]), (PG8_LAS unsigned*)(lds + (bufoff) + ldsw + _i * 8192), 16, 0, 0); } while (0)
; #define PG8_LDA(dst, b, h) do { _Pragma("unroll") for (int m = 0; m < 4; ++m) _Pragma("unroll") for (int k = 0; k < 2; ++k) dst[m][k] = *(const PG8_LAS bf16x8*)(lds + PG8_SA(b, h) + aoff + m * 2048 + k * 1024); } while (0)
; #define PG8_LDB(dst, b, h) do { _Pragma("unroll") for (int n = 0; n < 2; ++n) _Pragma("unroll") for (int k = 0; k < 2; ++k) dst[n][k] = *(const PG8_LAS bf16x8*)(lds + PG8_SB(b, h) + boff + n * 2048 + k * 1024); } while (0)
; #define PG8_MMA(ai, bj, At, Bt) do { __builtin_amdgcn_s_setprio(1); _Pragma("unroll") for (int m = 0; m < 4; ++m) _Pragma("unroll") for (int n = 0; n < 2; ++n) _Pragma("unroll") for (int k = 0; k < 2; ++k) \
;         acc[ai][bj][m][n] = __builtin_amdgcn_mfma_f32_16x16x32_bf16(Bt[n][k], At[m][k], acc[ai][bj][m][n], 0, 0, 0); __builtin_amdgcn_s_setprio(0); } while (0)
; #define PG8_WAIT_V(n) asm volatile("s_waitcnt vmcnt(" #n ")" ::: "memory")
; #define PG8_WAIT_L(n) asm volatile("s_waitcnt lgkmcnt(" #n ")" ::: "memory")
; #define PG8_BAR __builtin_amdgcn_s_barrier()
; #define PG8_SCHED __builtin_amdgcn_sched_barrier(0)
; template <class Epi, class Sched, bool ALIGN_EPI = false, bool SP2 = false>
; __device__ __forceinline__ void gemm_phase(PG8_LAS unsigned char* lds, const Gemm g, const Sched& S, const Epi& E, int tid_in) {
;     ...
;             PG8_WAIT_V(8); PG8_WAIT_L(0); PG8_BAR; PG8_MMA(1, 0, At, B0); PG8_MMA(1, 1, At, B1); PG8_BAR; PG8_SCHED;
;             PG8_LDB(B0, 1, 0); PG8_LDB(B1, 1, 1); PG8_SCHED; PG8_LDA(At, 1, 0); PG8_STAGE(PG8_SA(0, 1), a2 + hstep, voffA);
;             PG8_WAIT_V(8); PG8_WAIT_L(0); PG8_BAR; PG8_MMA(0, 0, At, B0); PG8_MMA(0, 1, At, B1); PG8_BAR; PG8_SCHED;
	s_setprio 1
	s_waitcnt lgkmcnt(0)
	v_mfma_f32_16x16x32_bf16 v[62:65], v[130:133], v[162:165], v[62:65]
	v_mfma_f32_16x16x32_bf16 v[58:61], v[138:141], v[162:165], v[58:61]
	v_mfma_f32_16x16x32_bf16 v[50:53], v[130:133], v[170:173], v[50:53]
	v_mfma_f32_16x16x32_bf16 v[42:45], v[138:141], v[170:173], v[42:45]
	v_mfma_f32_16x16x32_bf16 v[34:37], v[130:133], v[178:181], v[34:37]
	v_mfma_f32_16x16x32_bf16 v[24:27], v[138:141], v[178:181], v[24:27]
	v_mfma_f32_16x16x32_bf16 v[16:19], v[130:133], v[186:189], v[16:19]
	v_mfma_f32_16x16x32_bf16 v[8:11], v[138:141], v[186:189], v[8:11]
	v_mfma_f32_16x16x32_bf16 v[62:65], v[134:137], v[166:169], v[62:65]
	v_mfma_f32_16x16x32_bf16 v[58:61], v[142:145], v[166:169], v[58:61]
	v_mfma_f32_16x16x32_bf16 v[50:53], v[134:137], v[174:177], v[50:53]
	v_mfma_f32_16x16x32_bf16 v[42:45], v[142:145], v[174:177], v[42:45]
	v_mfma_f32_16x16x32_bf16 v[34:37], v[134:137], v[182:185], v[34:37]
	v_mfma_f32_16x16x32_bf16 v[24:27], v[142:145], v[182:185], v[24:27]
	v_mfma_f32_16x16x32_bf16 v[16:19], v[134:137], v[190:193], v[16:19]
	v_mfma_f32_16x16x32_bf16 v[8:11], v[142:145], v[190:193], v[8:11]
	s_setprio 0
	s_setprio 1
	v_mfma_f32_16x16x32_bf16 v[54:57], v[146:149], v[162:165], v[54:57]
	v_mfma_f32_16x16x32_bf16 v[46:49], v[154:157], v[162:165], v[46:49]
	v_mfma_f32_16x16x32_bf16 v[38:41], v[146:149], v[170:173], v[38:41]
	v_mfma_f32_16x16x32_bf16 v[28:31], v[154:157], v[170:173], v[28:31]
	v_mfma_f32_16x16x32_bf16 v[20:23], v[146:149], v[178:181], v[20:23]
	v_mfma_f32_16x16x32_bf16 v[12:15], v[154:157], v[178:181], v[12:15]
	v_mfma_f32_16x16x32_bf16 v[4:7], v[146:149], v[186:189], v[4:7]
	v_mfma_f32_16x16x32_bf16 v[0:3], v[154:157], v[186:189], v[0:3]
	v_mfma_f32_16x16x32_bf16 v[54:57], v[150:153], v[166:169], v[54:57]
	v_mfma_f32_16x16x32_bf16 v[46:49], v[158:161], v[166:169], v[46:49]
	v_mfma_f32_16x16x32_bf16 v[38:41], v[150:153], v[174:177], v[38:41]
	v_mfma_f32_16x16x32_bf16 v[28:31], v[158:161], v[174:177], v[28:31]
	v_mfma_f32_16x16x32_bf16 v[20:23], v[150:153], v[182:185], v[20:23]
	v_mfma_f32_16x16x32_bf16 v[12:15], v[158:161], v[182:185], v[12:15]
	v_mfma_f32_16x16x32_bf16 v[4:7], v[150:153], v[190:193], v[4:7]
	v_mfma_f32_16x16x32_bf16 v[0:3], v[158:161], v[190:193], v[0:3]
	s_setprio 0
	s_barrier
	s_add_i32 s52, 0, 0x18000
	s_add_i32 s53, 0, 0x1c000
	v_add_u32_e32 v142, s52, v248
	v_add_u32_e32 v158, s53, v248
	ds_read_b128 v[130:133], v142
	ds_read_b128 v[134:137], v142 offset:1024
	ds_read_b128 v[138:141], v142 offset:2048
	ds_read_b128 v[142:145], v142 offset:3072
	ds_read_b128 v[146:149], v158
	ds_read_b128 v[150:153], v158 offset:1024
	ds_read_b128 v[154:157], v158 offset:2048
	ds_read_b128 v[158:161], v158 offset:3072
	s_add_u32 s2, s28, 0xb0000
	s_addc_u32 s3, s29, 0
	s_mov_b32 m0, s40
	v_lshl_add_u64 v[222:223], s[2:3], 0, v[208:209]
	ds_read_b128 v[162:165], v250 offset:32768
	ds_read_b128 v[166:169], v250 offset:33792
	ds_read_b128 v[170:173], v250 offset:34816
	ds_read_b128 v[174:177], v250 offset:35840
	ds_read_b128 v[178:181], v250 offset:36864
	ds_read_b128 v[182:185], v250 offset:37888
	ds_read_b128 v[186:189], v250 offset:38912
	ds_read_b128 v[190:193], v250 offset:39936
	global_load_lds_dwordx4 v[222:223], off
	v_lshl_add_u64 v[222:223], s[2:3], 0, v[206:207]
	s_mov_b32 m0, s41
	s_nop 0
	global_load_lds_dwordx4 v[222:223], off
	s_waitcnt vmcnt(8)
	s_waitcnt lgkmcnt(0)
	s_barrier
	s_setprio 1
	s_waitcnt lgkmcnt(0)
	v_mfma_f32_16x16x32_bf16 v[126:129], v[130:133], v[162:165], v[126:129]
	v_mfma_f32_16x16x32_bf16 v[122:125], v[138:141], v[162:165], v[122:125]
	v_mfma_f32_16x16x32_bf16 v[114:117], v[130:133], v[170:173], v[114:117]
	v_mfma_f32_16x16x32_bf16 v[106:109], v[138:141], v[170:173], v[106:109]
	v_mfma_f32_16x16x32_bf16 v[98:101], v[130:133], v[178:181], v[98:101]
	v_mfma_f32_16x16x32_bf16 v[90:93], v[138:141], v[178:181], v[90:93]
	v_mfma_f32_16x16x32_bf16 v[82:85], v[130:133], v[186:189], v[82:85]
	v_mfma_f32_16x16x32_bf16 v[74:77], v[138:141], v[186:189], v[74:77]
	v_mfma_f32_16x16x32_bf16 v[126:129], v[134:137], v[166:169], v[126:129]
	v_mfma_f32_16x16x32_bf16 v[122:125], v[142:145], v[166:169], v[122:125]
	v_mfma_f32_16x16x32_bf16 v[114:117], v[134:137], v[174:177], v[114:117]
	v_mfma_f32_16x16x32_bf16 v[106:109], v[142:145], v[174:177], v[106:109]
	v_mfma_f32_16x16x32_bf16 v[98:101], v[134:137], v[182:185], v[98:101]
	v_mfma_f32_16x16x32_bf16 v[90:93], v[142:145], v[182:185], v[90:93]
	v_mfma_f32_16x16x32_bf16 v[82:85], v[134:137], v[190:193], v[82:85]
	v_mfma_f32_16x16x32_bf16 v[74:77], v[142:145], v[190:193], v[74:77]
	s_setprio 0
	s_setprio 1
	v_mfma_f32_16x16x32_bf16 v[118:121], v[146:149], v[162:165], v[118:121]
	v_mfma_f32_16x16x32_bf16 v[110:113], v[154:157], v[162:165], v[110:113]
	v_mfma_f32_16x16x32_bf16 v[102:105], v[146:149], v[170:173], v[102:105]
	v_mfma_f32_16x16x32_bf16 v[94:97], v[154:157], v[170:173], v[94:97]
	v_mfma_f32_16x16x32_bf16 v[86:89], v[146:149], v[178:181], v[86:89]
	v_mfma_f32_16x16x32_bf16 v[78:81], v[154:157], v[178:181], v[78:81]
	v_mfma_f32_16x16x32_bf16 v[70:73], v[146:149], v[186:189], v[70:73]
	v_mfma_f32_16x16x32_bf16 v[66:69], v[154:157], v[186:189], v[66:69]
	v_mfma_f32_16x16x32_bf16 v[118:121], v[150:153], v[166:169], v[118:121]
	v_mfma_f32_16x16x32_bf16 v[110:113], v[158:161], v[166:169], v[110:113]
	v_mfma_f32_16x16x32_bf16 v[102:105], v[150:153], v[174:177], v[102:105]
	v_mfma_f32_16x16x32_bf16 v[94:97], v[158:161], v[174:177], v[94:97]
	v_mfma_f32_16x16x32_bf16 v[86:89], v[150:153], v[182:185], v[86:89]
	v_mfma_f32_16x16x32_bf16 v[78:81], v[158:161], v[182:185], v[78:81]
	v_mfma_f32_16x16x32_bf16 v[70:73], v[150:153], v[190:193], v[70:73]
	v_mfma_f32_16x16x32_bf16 v[66:69], v[158:161], v[190:193], v[66:69]
	s_setprio 0
	s_barrier
; #define PG8_STAGE(bufoff, gbase, voff) do { _Pragma("unroll") for (int _i = 0; _i < 2; ++_i) \
;         __builtin_amdgcn_global_load_lds((const unsigned*)((const char*)(gbase) + (voff)[_i]), (PG8_LAS unsigned*)(lds + (bufoff) + ldsw + _i * 8192), 16, 0, 0); } while (0)
; #define PG8_LDA(dst, b, h) do { _Pragma("unroll") for (int m = 0; m < 4; ++m) _Pragma("unroll") for (int k = 0; k < 2; ++k) dst[m][k] = *(const PG8_LAS bf16x8*)(lds + PG8_SA(b, h) + aoff + m * 2048 + k * 1024); } while (0)
; #define PG8_MMA(ai, bj, At, Bt) do { __builtin_amdgcn_s_setprio(1); _Pragma("unroll") for (int m = 0; m < 4; ++m) _Pragma("unroll") for (int n = 0; n < 2; ++n) _Pragma("unroll") for (int k = 0; k < 2; ++k) \
;         acc[ai][bj][m][n] = __builtin_amdgcn_mfma_f32_16x16x32_bf16(Bt[n][k], At[m][k], acc[ai][bj][m][n], 0, 0, 0); __builtin_amdgcn_s_setprio(0); } while (0)
; #define PG8_WAIT_V(n) asm volatile("s_waitcnt vmcnt(" #n ")" ::: "memory")
; #define PG8_WAIT_L(n) asm volatile("s_waitcnt lgkmcnt(" #n ")" ::: "memory")
; #define PG8_BAR __builtin_amdgcn_s_barrier()
; #define PG8_SCHED __builtin_amdgcn_sched_barrier(0)
; template <class Epi, class Sched, bool ALIGN_EPI = false, bool SP2 = false>
; __device__ __forceinline__ void gemm_phase(PG8_LAS unsigned char* lds, const Gemm g, const Sched& S, const Epi& E, int tid_in) {
;     ...
;             PG8_LDA(At, 1, 1); PG8_STAGE(PG8_SB(1, 0), b3, voffB); PG8_STAGE(PG8_SB(1, 1), b3 + hstep, voffB); PG8_STAGE(PG8_SA(1, 0), a3, voffA);
;             PG8_WAIT_V(8); PG8_WAIT_L(0); PG8_BAR; PG8_MMA(1, 0, At, B0); PG8_MMA(1, 1, At, B1); PG8_BAR; PG8_SCHED;
;     ...
;         if constexpr (ALIGN_EPI) { if (wr == 0) PG8_BAR; }
	s_add_i32 s2, s52, s31
	v_lshl_add_u64 v[214:215], v[214:215], 0, s[84:85]
	s_mov_b32 m0, s2
	ds_read_b128 v[162:165], v250 offset:49152
	ds_read_b128 v[166:169], v250 offset:50176
	ds_read_b128 v[170:173], v250 offset:51200
	ds_read_b128 v[174:177], v250 offset:52224
	ds_read_b128 v[178:181], v250 offset:53248
	ds_read_b128 v[182:185], v250 offset:54272
	ds_read_b128 v[186:189], v250 offset:55296
	ds_read_b128 v[190:193], v250 offset:56320
	global_load_lds_dwordx4 v[214:215], off
	s_add_i32 m0, s2, 0x2000
	s_add_u32 s2, s26, 0xb0080
	v_lshl_add_u64 v[214:215], v[216:217], 0, s[84:85]
	s_addc_u32 s3, s27, 0
	s_add_i32 s26, s53, s31
	global_load_lds_dwordx4 v[214:215], off
	v_lshl_add_u64 v[214:215], s[2:3], 0, v[32:33]
	s_mov_b32 m0, s26
	s_nop 0
	global_load_lds_dwordx4 v[214:215], off
	v_lshl_add_u64 v[214:215], s[2:3], 0, v[204:205]
	s_add_i32 m0, s26, 0x2000
	s_nop 0
	global_load_lds_dwordx4 v[214:215], off
	v_lshl_add_u64 v[214:215], v[218:219], 0, s[84:85]
	s_mov_b32 m0, s42
	s_nop 0
	global_load_lds_dwordx4 v[214:215], off
	v_lshl_add_u64 v[214:215], v[220:221], 0, s[84:85]
	s_mov_b32 m0, s43
	s_nop 0
	global_load_lds_dwordx4 v[214:215], off
	s_waitcnt vmcnt(8)
	s_waitcnt lgkmcnt(0)
	s_barrier
	s_setprio 1
	s_waitcnt lgkmcnt(0)
	v_mfma_f32_16x16x32_bf16 v[62:65], v[130:133], v[162:165], v[62:65]
	v_mfma_f32_16x16x32_bf16 v[58:61], v[138:141], v[162:165], v[58:61]
	v_mfma_f32_16x16x32_bf16 v[50:53], v[130:133], v[170:173], v[50:53]
	v_mfma_f32_16x16x32_bf16 v[42:45], v[138:141], v[170:173], v[42:45]
	v_mfma_f32_16x16x32_bf16 v[34:37], v[130:133], v[178:181], v[34:37]
	v_mfma_f32_16x16x32_bf16 v[24:27], v[138:141], v[178:181], v[24:27]
	v_mfma_f32_16x16x32_bf16 v[16:19], v[130:133], v[186:189], v[16:19]
	v_mfma_f32_16x16x32_bf16 v[8:11], v[138:141], v[186:189], v[8:11]
	v_mfma_f32_16x16x32_bf16 v[62:65], v[134:137], v[166:169], v[62:65]
	v_mfma_f32_16x16x32_bf16 v[58:61], v[142:145], v[166:169], v[58:61]
	v_mfma_f32_16x16x32_bf16 v[50:53], v[134:137], v[174:177], v[50:53]
	v_mfma_f32_16x16x32_bf16 v[42:45], v[142:145], v[174:177], v[42:45]
	v_mfma_f32_16x16x32_bf16 v[34:37], v[134:137], v[182:185], v[34:37]
	v_mfma_f32_16x16x32_bf16 v[24:27], v[142:145], v[182:185], v[24:27]
	v_mfma_f32_16x16x32_bf16 v[16:19], v[134:137], v[190:193], v[16:19]
	v_mfma_f32_16x16x32_bf16 v[8:11], v[142:145], v[190:193], v[8:11]
	s_setprio 0
	s_setprio 1
	v_mfma_f32_16x16x32_bf16 v[54:57], v[146:149], v[162:165], v[54:57]
	v_mfma_f32_16x16x32_bf16 v[46:49], v[154:157], v[162:165], v[46:49]
	v_mfma_f32_16x16x32_bf16 v[38:41], v[146:149], v[170:173], v[38:41]
	v_mfma_f32_16x16x32_bf16 v[28:31], v[154:157], v[170:173], v[28:31]
	v_mfma_f32_16x16x32_bf16 v[20:23], v[146:149], v[178:181], v[20:23]
	v_mfma_f32_16x16x32_bf16 v[12:15], v[154:157], v[178:181], v[12:15]
	v_mfma_f32_16x16x32_bf16 v[4:7], v[146:149], v[186:189], v[4:7]
	v_mfma_f32_16x16x32_bf16 v[0:3], v[154:157], v[186:189], v[0:3]
	v_mfma_f32_16x16x32_bf16 v[54:57], v[150:153], v[166:169], v[54:57]
	v_mfma_f32_16x16x32_bf16 v[46:49], v[158:161], v[166:169], v[46:49]
	v_mfma_f32_16x16x32_bf16 v[38:41], v[150:153], v[174:177], v[38:41]
	v_mfma_f32_16x16x32_bf16 v[28:31], v[158:161], v[174:177], v[28:31]
	v_mfma_f32_16x16x32_bf16 v[20:23], v[150:153], v[182:185], v[20:23]
	v_mfma_f32_16x16x32_bf16 v[12:15], v[158:161], v[182:185], v[12:15]
	v_mfma_f32_16x16x32_bf16 v[4:7], v[150:153], v[190:193], v[4:7]
	v_mfma_f32_16x16x32_bf16 v[0:3], v[158:161], v[190:193], v[0:3]
	s_setprio 0
	s_barrier
	s_add_i32 s51, s51, 2
	s_add_u32 s49, s49, 0x100
	s_addc_u32 s50, s50, 0
	s_cmp_gt_u32 s51, 41
	s_mov_b64 s[2:3], s[6:7]
	s_cbranch_scc0 .LBB0_1010
	s_and_b64 vcc, exec, s[18:19]
	s_cbranch_vccz .LBB0_1013
	s_barrier
.LBB0_1013:
	s_cmp_eq_u64 s[18:19], 0
	s_cbranch_scc0 .Lge_np5
	s_setprio 1
